# nt (streaming) hint on the read-once f32 weight loads of P0 (transposes and adaLN weights)
# baseline (speedup 1.0000x reference)
.LBB0_34:
	s_or_saveexec_b64 s[0:1], s[52:53]
	s_mov_b64 s[52:53], 0
	s_xor_b64 exec, exec, s[0:1]
	s_cbranch_execz .LBB0_42
	v_mov_b32_e32 v2, v80
	v_mov_b32_e32 v3, v7
	v_mov_b32_e32 v4, s65
	v_mov_b32_e32 v5, s66
	v_mov_b32_e32 v8, s72
	ds_read_b64 v[252:253], v4
	ds_read_b64 v[254:255], v5
	ds_read_b64 v[194:195], v8
	v_lshlrev_b32_e32 v8, 2, v3
	v_lshlrev_b32_e32 v4, 2, v60
	s_waitcnt lgkmcnt(0)
	v_add_co_u32_e32 v252, vcc, v252, v8
	v_addc_co_u32_e32 v253, vcc, 0, v253, vcc
	v_add_co_u32_e32 v254, vcc, v254, v8
	v_addc_co_u32_e32 v255, vcc, 0, v255, vcc
	v_add_co_u32_e32 v194, vcc, v194, v10
	v_addc_co_u32_e32 v195, vcc, v195, v11, vcc
	v_add_co_u32_e32 v194, vcc, v194, v4
	v_addc_co_u32_e32 v195, vcc, 0, v195, vcc
	global_load_dword v214, v[252:253], off
	global_load_dword v215, v[252:253], off offset:1024
	global_load_dword v216, v[252:253], off offset:2048
	global_load_dword v217, v[252:253], off offset:3072
	v_add_co_u32_e32 v252, vcc, 0x1000, v252
	v_addc_co_u32_e32 v253, vcc, 0, v253, vcc
	global_load_dword v218, v[252:253], off
	global_load_dword v219, v[252:253], off offset:1024
	global_load_dword v220, v[252:253], off offset:2048
	global_load_dword v221, v[252:253], off offset:3072
	v_add_co_u32_e32 v252, vcc, 0x1000, v252
	v_addc_co_u32_e32 v253, vcc, 0, v253, vcc
	global_load_dword v222, v[252:253], off
	global_load_dword v223, v[252:253], off offset:1024
	global_load_dword v224, v[252:253], off offset:2048
	global_load_dword v225, v[252:253], off offset:3072
	v_add_co_u32_e32 v252, vcc, 0x1000, v252
	v_addc_co_u32_e32 v253, vcc, 0, v253, vcc
	global_load_dword v226, v[252:253], off
	global_load_dword v227, v[252:253], off offset:1024
	global_load_dword v228, v[252:253], off offset:2048
	global_load_dword v229, v[252:253], off offset:3072
	v_add_co_u32_e32 v252, vcc, 0x1000, v252
	v_addc_co_u32_e32 v253, vcc, 0, v253, vcc
	global_load_dword v230, v[252:253], off
	global_load_dword v231, v[252:253], off offset:1024
	global_load_dword v232, v[252:253], off offset:2048
	global_load_dword v233, v[252:253], off offset:3072
	v_add_co_u32_e32 v252, vcc, 0x1000, v252
	v_addc_co_u32_e32 v253, vcc, 0, v253, vcc
	global_load_dword v234, v[252:253], off
	global_load_dword v235, v[252:253], off offset:1024
	global_load_dword v236, v[252:253], off offset:2048
	global_load_dword v237, v[252:253], off offset:3072
	v_add_co_u32_e32 v252, vcc, 0x1000, v252
	v_addc_co_u32_e32 v253, vcc, 0, v253, vcc
	global_load_dword v239, v[252:253], off
	global_load_dword v240, v[252:253], off offset:1024
	global_load_dword v241, v[252:253], off offset:2048
	global_load_dword v242, v[252:253], off offset:3072
	v_add_co_u32_e32 v252, vcc, 0x1000, v252
	v_addc_co_u32_e32 v253, vcc, 0, v253, vcc
	global_load_dword v243, v[252:253], off
	global_load_dword v244, v[252:253], off offset:1024
	global_load_dword v245, v[252:253], off offset:2048
	global_load_dword v246, v[252:253], off offset:3072
	global_load_dword v247, v[254:255], off
	global_load_dword v248, v[254:255], off offset:1024
	global_load_dword v249, v[254:255], off offset:2048
	global_load_dword v250, v[254:255], off offset:3072
	global_load_dword v150, v[194:195], off nt
	v_add_co_u32_e32 v194, vcc, 0x6000, v194
	v_addc_co_u32_e32 v195, vcc, 0, v195, vcc
	global_load_dword v151, v[194:195], off nt
	v_add_co_u32_e32 v194, vcc, 0x6000, v194
	v_addc_co_u32_e32 v195, vcc, 0, v195, vcc
	global_load_dword v152, v[194:195], off nt
	v_add_co_u32_e32 v194, vcc, 0x6000, v194
	v_addc_co_u32_e32 v195, vcc, 0, v195, vcc
	global_load_dword v153, v[194:195], off nt
	v_add_co_u32_e32 v194, vcc, 0x6000, v194
	v_addc_co_u32_e32 v195, vcc, 0, v195, vcc
	global_load_dword v154, v[194:195], off nt
	v_add_co_u32_e32 v194, vcc, 0x6000, v194
	v_addc_co_u32_e32 v195, vcc, 0, v195, vcc
	global_load_dword v155, v[194:195], off nt
	v_add_co_u32_e32 v194, vcc, 0x6000, v194
	v_addc_co_u32_e32 v195, vcc, 0, v195, vcc
	global_load_dword v156, v[194:195], off nt
	v_add_co_u32_e32 v194, vcc, 0x6000, v194
	v_addc_co_u32_e32 v195, vcc, 0, v195, vcc
	global_load_dword v157, v[194:195], off nt
	v_add_co_u32_e32 v194, vcc, 0x6000, v194
	v_addc_co_u32_e32 v195, vcc, 0, v195, vcc
	global_load_dword v158, v[194:195], off nt
	v_add_co_u32_e32 v194, vcc, 0x6000, v194
	v_addc_co_u32_e32 v195, vcc, 0, v195, vcc
	global_load_dword v159, v[194:195], off nt
	v_add_co_u32_e32 v194, vcc, 0x6000, v194
	v_addc_co_u32_e32 v195, vcc, 0, v195, vcc
	global_load_dword v160, v[194:195], off nt
	v_add_co_u32_e32 v194, vcc, 0x6000, v194
	v_addc_co_u32_e32 v195, vcc, 0, v195, vcc
	global_load_dword v161, v[194:195], off nt
	v_add_co_u32_e32 v194, vcc, 0x6000, v194
	v_addc_co_u32_e32 v195, vcc, 0, v195, vcc
	global_load_dword v162, v[194:195], off nt
	v_add_co_u32_e32 v194, vcc, 0x6000, v194
	v_addc_co_u32_e32 v195, vcc, 0, v195, vcc
	global_load_dword v163, v[194:195], off nt
	v_add_co_u32_e32 v194, vcc, 0x6000, v194
	v_addc_co_u32_e32 v195, vcc, 0, v195, vcc
	global_load_dword v164, v[194:195], off nt
	v_add_co_u32_e32 v194, vcc, 0x6000, v194
	v_addc_co_u32_e32 v195, vcc, 0, v195, vcc
	global_load_dword v165, v[194:195], off nt
	v_add_co_u32_e32 v194, vcc, 0x6000, v194
	v_addc_co_u32_e32 v195, vcc, 0, v195, vcc
	global_load_dword v166, v[194:195], off nt
	v_add_co_u32_e32 v194, vcc, 0x6000, v194
	v_addc_co_u32_e32 v195, vcc, 0, v195, vcc
	global_load_dword v167, v[194:195], off nt
	v_add_co_u32_e32 v194, vcc, 0x6000, v194
	v_addc_co_u32_e32 v195, vcc, 0, v195, vcc
	global_load_dword v168, v[194:195], off nt
	v_add_co_u32_e32 v194, vcc, 0x6000, v194
	v_addc_co_u32_e32 v195, vcc, 0, v195, vcc
	global_load_dword v169, v[194:195], off nt
	v_add_co_u32_e32 v194, vcc, 0x6000, v194
	v_addc_co_u32_e32 v195, vcc, 0, v195, vcc
	global_load_dword v170, v[194:195], off nt
	v_add_co_u32_e32 v194, vcc, 0x6000, v194
	v_addc_co_u32_e32 v195, vcc, 0, v195, vcc
	global_load_dword v171, v[194:195], off nt
	v_add_co_u32_e32 v194, vcc, 0x6000, v194
	v_addc_co_u32_e32 v195, vcc, 0, v195, vcc
	global_load_dword v172, v[194:195], off nt
	v_add_co_u32_e32 v194, vcc, 0x6000, v194
	v_addc_co_u32_e32 v195, vcc, 0, v195, vcc
	global_load_dword v173, v[194:195], off nt
	v_add_co_u32_e32 v194, vcc, 0x6000, v194
	v_addc_co_u32_e32 v195, vcc, 0, v195, vcc
	s_waitcnt vmcnt(59)
	v_mov_b32_e32 v4, v214
	v_mul_f32_e32 v5, 0xbfb8aa3b, v4
	v_fma_f32 v8, v4, s67, -v5
	v_rndne_f32_e32 v23, v5
	v_fmac_f32_e32 v8, 0xb2a5705f, v4
	v_sub_f32_e32 v5, v5, v23
	v_add_f32_e32 v5, v5, v8
	v_cvt_i32_f32_e32 v23, v23
	v_exp_f32_e32 v5, v5
	v_cmp_nlt_f32_e32 vcc, s68, v4
	v_ldexp_f32 v5, v5, v23
	s_nop 0
	v_cndmask_b32_e32 v5, 0, v5, vcc
	v_cmp_ngt_f32_e32 vcc, s69, v4
	s_nop 1
	v_cndmask_b32_e32 v5, v95, v5, vcc
	v_add_f32_e32 v5, 1.0, v5
	v_div_scale_f32 v8, s[54:55], v5, v5, v4
	v_rcp_f32_e32 v23, v8
	v_div_scale_f32 v61, vcc, v4, v5, v4
	v_fma_f32 v65, -v8, v23, 1.0
	v_fmac_f32_e32 v23, v65, v23
	v_mul_f32_e32 v65, v61, v23
	v_fma_f32 v66, -v8, v65, v61
	v_fmac_f32_e32 v65, v66, v23
	v_fma_f32 v8, -v8, v65, v61
	v_div_fmas_f32 v8, v8, v23, v65
	v_div_fixup_f32 v4, v8, v5, v4
	ds_write_b32 v2, v4
	s_waitcnt vmcnt(58)
	v_mov_b32_e32 v4, v215
	v_mul_f32_e32 v5, 0xbfb8aa3b, v4
	v_fma_f32 v8, v4, s67, -v5
	v_rndne_f32_e32 v23, v5
	v_fmac_f32_e32 v8, 0xb2a5705f, v4
	v_sub_f32_e32 v5, v5, v23
	v_add_f32_e32 v5, v5, v8
	v_cvt_i32_f32_e32 v23, v23
	v_exp_f32_e32 v5, v5
	v_cmp_nlt_f32_e32 vcc, s68, v4
	v_ldexp_f32 v5, v5, v23
	s_nop 0
	v_cndmask_b32_e32 v5, 0, v5, vcc
	v_cmp_ngt_f32_e32 vcc, s69, v4
	s_nop 1
	v_cndmask_b32_e32 v5, v95, v5, vcc
	v_add_f32_e32 v5, 1.0, v5
	v_div_scale_f32 v8, s[54:55], v5, v5, v4
	v_rcp_f32_e32 v23, v8
	v_div_scale_f32 v61, vcc, v4, v5, v4
	v_fma_f32 v65, -v8, v23, 1.0
	v_fmac_f32_e32 v23, v65, v23
	v_mul_f32_e32 v65, v61, v23
	v_fma_f32 v66, -v8, v65, v61
	v_fmac_f32_e32 v65, v66, v23
	v_fma_f32 v8, -v8, v65, v61
	v_div_fmas_f32 v8, v8, v23, v65
	v_div_fixup_f32 v4, v8, v5, v4
	ds_write_b32 v2, v4 offset:1024
	s_waitcnt vmcnt(57)
	v_mov_b32_e32 v4, v216
	v_mul_f32_e32 v5, 0xbfb8aa3b, v4
	v_fma_f32 v8, v4, s67, -v5
	v_rndne_f32_e32 v23, v5
	v_fmac_f32_e32 v8, 0xb2a5705f, v4
	v_sub_f32_e32 v5, v5, v23
	v_add_f32_e32 v5, v5, v8
	v_cvt_i32_f32_e32 v23, v23
	v_exp_f32_e32 v5, v5
	v_cmp_nlt_f32_e32 vcc, s68, v4
	v_ldexp_f32 v5, v5, v23
	s_nop 0
	v_cndmask_b32_e32 v5, 0, v5, vcc
	v_cmp_ngt_f32_e32 vcc, s69, v4
	s_nop 1
	v_cndmask_b32_e32 v5, v95, v5, vcc
	v_add_f32_e32 v5, 1.0, v5
	v_div_scale_f32 v8, s[54:55], v5, v5, v4
	v_rcp_f32_e32 v23, v8
	v_div_scale_f32 v61, vcc, v4, v5, v4
	v_fma_f32 v65, -v8, v23, 1.0
	v_fmac_f32_e32 v23, v65, v23
	v_mul_f32_e32 v65, v61, v23
	v_fma_f32 v66, -v8, v65, v61
	v_fmac_f32_e32 v65, v66, v23
	v_fma_f32 v8, -v8, v65, v61
	v_div_fmas_f32 v8, v8, v23, v65
	v_div_fixup_f32 v4, v8, v5, v4
	ds_write_b32 v2, v4 offset:2048
	s_waitcnt vmcnt(56)
	v_mov_b32_e32 v4, v217
	v_mul_f32_e32 v5, 0xbfb8aa3b, v4
	v_fma_f32 v8, v4, s67, -v5
	v_rndne_f32_e32 v23, v5
	v_fmac_f32_e32 v8, 0xb2a5705f, v4
	v_sub_f32_e32 v5, v5, v23
	v_add_f32_e32 v5, v5, v8
	v_cvt_i32_f32_e32 v23, v23
	v_exp_f32_e32 v5, v5
	v_cmp_nlt_f32_e32 vcc, s68, v4
	v_ldexp_f32 v5, v5, v23
	s_nop 0
	v_cndmask_b32_e32 v5, 0, v5, vcc
	v_cmp_ngt_f32_e32 vcc, s69, v4
	s_nop 1
	v_cndmask_b32_e32 v5, v95, v5, vcc
	v_add_f32_e32 v5, 1.0, v5
	v_div_scale_f32 v8, s[54:55], v5, v5, v4
	v_rcp_f32_e32 v23, v8
	v_div_scale_f32 v61, vcc, v4, v5, v4
	v_fma_f32 v65, -v8, v23, 1.0
	v_fmac_f32_e32 v23, v65, v23
	v_mul_f32_e32 v65, v61, v23
	v_fma_f32 v66, -v8, v65, v61
	v_fmac_f32_e32 v65, v66, v23
	v_fma_f32 v8, -v8, v65, v61
	v_div_fmas_f32 v8, v8, v23, v65
	v_div_fixup_f32 v4, v8, v5, v4
	ds_write_b32 v2, v4 offset:3072
	s_waitcnt vmcnt(55)
	v_mov_b32_e32 v4, v218
	v_mul_f32_e32 v5, 0xbfb8aa3b, v4
	v_fma_f32 v8, v4, s67, -v5
	v_rndne_f32_e32 v23, v5
	v_fmac_f32_e32 v8, 0xb2a5705f, v4
	v_sub_f32_e32 v5, v5, v23
	v_add_f32_e32 v5, v5, v8
	v_cvt_i32_f32_e32 v23, v23
	v_exp_f32_e32 v5, v5
	v_cmp_nlt_f32_e32 vcc, s68, v4
	v_ldexp_f32 v5, v5, v23
	s_nop 0
	v_cndmask_b32_e32 v5, 0, v5, vcc
	v_cmp_ngt_f32_e32 vcc, s69, v4
	s_nop 1
	v_cndmask_b32_e32 v5, v95, v5, vcc
	v_add_f32_e32 v5, 1.0, v5
	v_div_scale_f32 v8, s[54:55], v5, v5, v4
	v_rcp_f32_e32 v23, v8
	v_div_scale_f32 v61, vcc, v4, v5, v4
	v_fma_f32 v65, -v8, v23, 1.0
	v_fmac_f32_e32 v23, v65, v23
	v_mul_f32_e32 v65, v61, v23
	v_fma_f32 v66, -v8, v65, v61
	v_fmac_f32_e32 v65, v66, v23
	v_fma_f32 v8, -v8, v65, v61
	v_div_fmas_f32 v8, v8, v23, v65
	v_div_fixup_f32 v4, v8, v5, v4
	ds_write_b32 v2, v4 offset:4096
	s_waitcnt vmcnt(54)
	v_mov_b32_e32 v4, v219
	v_mul_f32_e32 v5, 0xbfb8aa3b, v4
	v_fma_f32 v8, v4, s67, -v5
	v_rndne_f32_e32 v23, v5
	v_fmac_f32_e32 v8, 0xb2a5705f, v4
	v_sub_f32_e32 v5, v5, v23
	v_add_f32_e32 v5, v5, v8
	v_cvt_i32_f32_e32 v23, v23
	v_exp_f32_e32 v5, v5
	v_cmp_nlt_f32_e32 vcc, s68, v4
	v_ldexp_f32 v5, v5, v23
	s_nop 0
	v_cndmask_b32_e32 v5, 0, v5, vcc
	v_cmp_ngt_f32_e32 vcc, s69, v4
	s_nop 1
	v_cndmask_b32_e32 v5, v95, v5, vcc
	v_add_f32_e32 v5, 1.0, v5
	v_div_scale_f32 v8, s[54:55], v5, v5, v4
	v_rcp_f32_e32 v23, v8
	v_div_scale_f32 v61, vcc, v4, v5, v4
	v_fma_f32 v65, -v8, v23, 1.0
	v_fmac_f32_e32 v23, v65, v23
	v_mul_f32_e32 v65, v61, v23
	v_fma_f32 v66, -v8, v65, v61
	v_fmac_f32_e32 v65, v66, v23
	v_fma_f32 v8, -v8, v65, v61
	v_div_fmas_f32 v8, v8, v23, v65
	v_div_fixup_f32 v4, v8, v5, v4
	ds_write_b32 v2, v4 offset:5120
	s_waitcnt vmcnt(53)
	v_mov_b32_e32 v4, v220
	v_mul_f32_e32 v5, 0xbfb8aa3b, v4
	v_fma_f32 v8, v4, s67, -v5
	v_rndne_f32_e32 v23, v5
	v_fmac_f32_e32 v8, 0xb2a5705f, v4
	v_sub_f32_e32 v5, v5, v23
	v_add_f32_e32 v5, v5, v8
	v_cvt_i32_f32_e32 v23, v23
	v_exp_f32_e32 v5, v5
	v_cmp_nlt_f32_e32 vcc, s68, v4
	v_ldexp_f32 v5, v5, v23
	s_nop 0
	v_cndmask_b32_e32 v5, 0, v5, vcc
	v_cmp_ngt_f32_e32 vcc, s69, v4
	s_nop 1
	v_cndmask_b32_e32 v5, v95, v5, vcc
	v_add_f32_e32 v5, 1.0, v5
	v_div_scale_f32 v8, s[54:55], v5, v5, v4
	v_rcp_f32_e32 v23, v8
	v_div_scale_f32 v61, vcc, v4, v5, v4
	v_fma_f32 v65, -v8, v23, 1.0
	v_fmac_f32_e32 v23, v65, v23
	v_mul_f32_e32 v65, v61, v23
	v_fma_f32 v66, -v8, v65, v61
	v_fmac_f32_e32 v65, v66, v23
	v_fma_f32 v8, -v8, v65, v61
	v_div_fmas_f32 v8, v8, v23, v65
	v_div_fixup_f32 v4, v8, v5, v4
	ds_write_b32 v2, v4 offset:6144
	s_waitcnt vmcnt(52)
	v_mov_b32_e32 v4, v221
	v_mul_f32_e32 v5, 0xbfb8aa3b, v4
	v_fma_f32 v8, v4, s67, -v5
	v_rndne_f32_e32 v23, v5
	v_fmac_f32_e32 v8, 0xb2a5705f, v4
	v_sub_f32_e32 v5, v5, v23
	v_add_f32_e32 v5, v5, v8
	v_cvt_i32_f32_e32 v23, v23
	v_exp_f32_e32 v5, v5
	v_cmp_nlt_f32_e32 vcc, s68, v4
	v_ldexp_f32 v5, v5, v23
	s_nop 0
	v_cndmask_b32_e32 v5, 0, v5, vcc
	v_cmp_ngt_f32_e32 vcc, s69, v4
	s_nop 1
	v_cndmask_b32_e32 v5, v95, v5, vcc
	v_add_f32_e32 v5, 1.0, v5
	v_div_scale_f32 v8, s[54:55], v5, v5, v4
	v_rcp_f32_e32 v23, v8
	v_div_scale_f32 v61, vcc, v4, v5, v4
	v_fma_f32 v65, -v8, v23, 1.0
	v_fmac_f32_e32 v23, v65, v23
	v_mul_f32_e32 v65, v61, v23
	v_fma_f32 v66, -v8, v65, v61
	v_fmac_f32_e32 v65, v66, v23
	v_fma_f32 v8, -v8, v65, v61
	v_div_fmas_f32 v8, v8, v23, v65
	v_div_fixup_f32 v4, v8, v5, v4
	ds_write_b32 v2, v4 offset:7168
	s_waitcnt vmcnt(51)
	v_mov_b32_e32 v4, v222
	v_mul_f32_e32 v5, 0xbfb8aa3b, v4
	v_fma_f32 v8, v4, s67, -v5
	v_rndne_f32_e32 v23, v5
	v_fmac_f32_e32 v8, 0xb2a5705f, v4
	v_sub_f32_e32 v5, v5, v23
	v_add_f32_e32 v5, v5, v8
	v_cvt_i32_f32_e32 v23, v23
	v_exp_f32_e32 v5, v5
	v_cmp_nlt_f32_e32 vcc, s68, v4
	v_ldexp_f32 v5, v5, v23
	s_nop 0
	v_cndmask_b32_e32 v5, 0, v5, vcc
	v_cmp_ngt_f32_e32 vcc, s69, v4
	s_nop 1
	v_cndmask_b32_e32 v5, v95, v5, vcc
	v_add_f32_e32 v5, 1.0, v5
	v_div_scale_f32 v8, s[54:55], v5, v5, v4
	v_rcp_f32_e32 v23, v8
	v_div_scale_f32 v61, vcc, v4, v5, v4
	v_fma_f32 v65, -v8, v23, 1.0
	v_fmac_f32_e32 v23, v65, v23
	v_mul_f32_e32 v65, v61, v23
	v_fma_f32 v66, -v8, v65, v61
	v_fmac_f32_e32 v65, v66, v23
	v_fma_f32 v8, -v8, v65, v61
	v_div_fmas_f32 v8, v8, v23, v65
	v_div_fixup_f32 v4, v8, v5, v4
	ds_write_b32 v2, v4 offset:8192
	s_waitcnt vmcnt(50)
	v_mov_b32_e32 v4, v223
	v_mul_f32_e32 v5, 0xbfb8aa3b, v4
	v_fma_f32 v8, v4, s67, -v5
	v_rndne_f32_e32 v23, v5
	v_fmac_f32_e32 v8, 0xb2a5705f, v4
	v_sub_f32_e32 v5, v5, v23
	v_add_f32_e32 v5, v5, v8
	v_cvt_i32_f32_e32 v23, v23
	v_exp_f32_e32 v5, v5
	v_cmp_nlt_f32_e32 vcc, s68, v4
	v_ldexp_f32 v5, v5, v23
	s_nop 0
	v_cndmask_b32_e32 v5, 0, v5, vcc
	v_cmp_ngt_f32_e32 vcc, s69, v4
	s_nop 1
	v_cndmask_b32_e32 v5, v95, v5, vcc
	v_add_f32_e32 v5, 1.0, v5
	v_div_scale_f32 v8, s[54:55], v5, v5, v4
	v_rcp_f32_e32 v23, v8
	v_div_scale_f32 v61, vcc, v4, v5, v4
	v_fma_f32 v65, -v8, v23, 1.0
	v_fmac_f32_e32 v23, v65, v23
	v_mul_f32_e32 v65, v61, v23
	v_fma_f32 v66, -v8, v65, v61
	v_fmac_f32_e32 v65, v66, v23
	v_fma_f32 v8, -v8, v65, v61
	v_div_fmas_f32 v8, v8, v23, v65
	v_div_fixup_f32 v4, v8, v5, v4
	ds_write_b32 v2, v4 offset:9216
	s_waitcnt vmcnt(49)
	v_mov_b32_e32 v4, v224
	v_mul_f32_e32 v5, 0xbfb8aa3b, v4
	v_fma_f32 v8, v4, s67, -v5
	v_rndne_f32_e32 v23, v5
	v_fmac_f32_e32 v8, 0xb2a5705f, v4
	v_sub_f32_e32 v5, v5, v23
	v_add_f32_e32 v5, v5, v8
	v_cvt_i32_f32_e32 v23, v23
	v_exp_f32_e32 v5, v5
	v_cmp_nlt_f32_e32 vcc, s68, v4
	v_ldexp_f32 v5, v5, v23
	s_nop 0
	v_cndmask_b32_e32 v5, 0, v5, vcc
	v_cmp_ngt_f32_e32 vcc, s69, v4
	s_nop 1
	v_cndmask_b32_e32 v5, v95, v5, vcc
	v_add_f32_e32 v5, 1.0, v5
	v_div_scale_f32 v8, s[54:55], v5, v5, v4
	v_rcp_f32_e32 v23, v8
	v_div_scale_f32 v61, vcc, v4, v5, v4
	v_fma_f32 v65, -v8, v23, 1.0
	v_fmac_f32_e32 v23, v65, v23
	v_mul_f32_e32 v65, v61, v23
	v_fma_f32 v66, -v8, v65, v61
	v_fmac_f32_e32 v65, v66, v23
	v_fma_f32 v8, -v8, v65, v61
	v_div_fmas_f32 v8, v8, v23, v65
	v_div_fixup_f32 v4, v8, v5, v4
	ds_write_b32 v2, v4 offset:10240
	s_waitcnt vmcnt(48)
	v_mov_b32_e32 v4, v225
	v_mul_f32_e32 v5, 0xbfb8aa3b, v4
	v_fma_f32 v8, v4, s67, -v5
	v_rndne_f32_e32 v23, v5
	v_fmac_f32_e32 v8, 0xb2a5705f, v4
	v_sub_f32_e32 v5, v5, v23
	v_add_f32_e32 v5, v5, v8
	v_cvt_i32_f32_e32 v23, v23
	v_exp_f32_e32 v5, v5
	v_cmp_nlt_f32_e32 vcc, s68, v4
	v_ldexp_f32 v5, v5, v23
	s_nop 0
	v_cndmask_b32_e32 v5, 0, v5, vcc
	v_cmp_ngt_f32_e32 vcc, s69, v4
	s_nop 1
	v_cndmask_b32_e32 v5, v95, v5, vcc
	v_add_f32_e32 v5, 1.0, v5
	v_div_scale_f32 v8, s[54:55], v5, v5, v4
	v_rcp_f32_e32 v23, v8
	v_div_scale_f32 v61, vcc, v4, v5, v4
	v_fma_f32 v65, -v8, v23, 1.0
	v_fmac_f32_e32 v23, v65, v23
	v_mul_f32_e32 v65, v61, v23
	v_fma_f32 v66, -v8, v65, v61
	v_fmac_f32_e32 v65, v66, v23
	v_fma_f32 v8, -v8, v65, v61
	v_div_fmas_f32 v8, v8, v23, v65
	v_div_fixup_f32 v4, v8, v5, v4
	ds_write_b32 v2, v4 offset:11264
	s_waitcnt vmcnt(47)
	v_mov_b32_e32 v4, v226
	v_mul_f32_e32 v5, 0xbfb8aa3b, v4
	v_fma_f32 v8, v4, s67, -v5
	v_rndne_f32_e32 v23, v5
	v_fmac_f32_e32 v8, 0xb2a5705f, v4
	v_sub_f32_e32 v5, v5, v23
	v_add_f32_e32 v5, v5, v8
	v_cvt_i32_f32_e32 v23, v23
	v_exp_f32_e32 v5, v5
	v_cmp_nlt_f32_e32 vcc, s68, v4
	v_ldexp_f32 v5, v5, v23
	s_nop 0
	v_cndmask_b32_e32 v5, 0, v5, vcc
	v_cmp_ngt_f32_e32 vcc, s69, v4
	s_nop 1
	v_cndmask_b32_e32 v5, v95, v5, vcc
	v_add_f32_e32 v5, 1.0, v5
	v_div_scale_f32 v8, s[54:55], v5, v5, v4
	v_rcp_f32_e32 v23, v8
	v_div_scale_f32 v61, vcc, v4, v5, v4
	v_fma_f32 v65, -v8, v23, 1.0
	v_fmac_f32_e32 v23, v65, v23
	v_mul_f32_e32 v65, v61, v23
	v_fma_f32 v66, -v8, v65, v61
	v_fmac_f32_e32 v65, v66, v23
	v_fma_f32 v8, -v8, v65, v61
	v_div_fmas_f32 v8, v8, v23, v65
	v_div_fixup_f32 v4, v8, v5, v4
	ds_write_b32 v2, v4 offset:12288
	s_waitcnt vmcnt(46)
	v_mov_b32_e32 v4, v227
	v_mul_f32_e32 v5, 0xbfb8aa3b, v4
	v_fma_f32 v8, v4, s67, -v5
	v_rndne_f32_e32 v23, v5
	v_fmac_f32_e32 v8, 0xb2a5705f, v4
	v_sub_f32_e32 v5, v5, v23
	v_add_f32_e32 v5, v5, v8
	v_cvt_i32_f32_e32 v23, v23
	v_exp_f32_e32 v5, v5
	v_cmp_nlt_f32_e32 vcc, s68, v4
	v_ldexp_f32 v5, v5, v23
	s_nop 0
	v_cndmask_b32_e32 v5, 0, v5, vcc
	v_cmp_ngt_f32_e32 vcc, s69, v4
	s_nop 1
	v_cndmask_b32_e32 v5, v95, v5, vcc
	v_add_f32_e32 v5, 1.0, v5
	v_div_scale_f32 v8, s[54:55], v5, v5, v4
	v_rcp_f32_e32 v23, v8
	v_div_scale_f32 v61, vcc, v4, v5, v4
	v_fma_f32 v65, -v8, v23, 1.0
	v_fmac_f32_e32 v23, v65, v23
	v_mul_f32_e32 v65, v61, v23
	v_fma_f32 v66, -v8, v65, v61
	v_fmac_f32_e32 v65, v66, v23
	v_fma_f32 v8, -v8, v65, v61
	v_div_fmas_f32 v8, v8, v23, v65
	v_div_fixup_f32 v4, v8, v5, v4
	ds_write_b32 v2, v4 offset:13312
	s_waitcnt vmcnt(45)
	v_mov_b32_e32 v4, v228
	v_mul_f32_e32 v5, 0xbfb8aa3b, v4
	v_fma_f32 v8, v4, s67, -v5
	v_rndne_f32_e32 v23, v5
	v_fmac_f32_e32 v8, 0xb2a5705f, v4
	v_sub_f32_e32 v5, v5, v23
	v_add_f32_e32 v5, v5, v8
	v_cvt_i32_f32_e32 v23, v23
	v_exp_f32_e32 v5, v5
	v_cmp_nlt_f32_e32 vcc, s68, v4
	v_ldexp_f32 v5, v5, v23
	s_nop 0
	v_cndmask_b32_e32 v5, 0, v5, vcc
	v_cmp_ngt_f32_e32 vcc, s69, v4
	s_nop 1
	v_cndmask_b32_e32 v5, v95, v5, vcc
	v_add_f32_e32 v5, 1.0, v5
	v_div_scale_f32 v8, s[54:55], v5, v5, v4
	v_rcp_f32_e32 v23, v8
	v_div_scale_f32 v61, vcc, v4, v5, v4
	v_fma_f32 v65, -v8, v23, 1.0
	v_fmac_f32_e32 v23, v65, v23
	v_mul_f32_e32 v65, v61, v23
	v_fma_f32 v66, -v8, v65, v61
	v_fmac_f32_e32 v65, v66, v23
	v_fma_f32 v8, -v8, v65, v61
	v_div_fmas_f32 v8, v8, v23, v65
	v_div_fixup_f32 v4, v8, v5, v4
	ds_write_b32 v2, v4 offset:14336
	s_waitcnt vmcnt(44)
	v_mov_b32_e32 v4, v229
	v_mul_f32_e32 v5, 0xbfb8aa3b, v4
	v_fma_f32 v8, v4, s67, -v5
	v_rndne_f32_e32 v23, v5
	v_fmac_f32_e32 v8, 0xb2a5705f, v4
	v_sub_f32_e32 v5, v5, v23
	v_add_f32_e32 v5, v5, v8
	v_cvt_i32_f32_e32 v23, v23
	v_exp_f32_e32 v5, v5
	v_cmp_nlt_f32_e32 vcc, s68, v4
	v_ldexp_f32 v5, v5, v23
	s_nop 0
	v_cndmask_b32_e32 v5, 0, v5, vcc
	v_cmp_ngt_f32_e32 vcc, s69, v4
	s_nop 1
	v_cndmask_b32_e32 v5, v95, v5, vcc
	v_add_f32_e32 v5, 1.0, v5
	v_div_scale_f32 v8, s[54:55], v5, v5, v4
	v_rcp_f32_e32 v23, v8
	v_div_scale_f32 v61, vcc, v4, v5, v4
	v_fma_f32 v65, -v8, v23, 1.0
	v_fmac_f32_e32 v23, v65, v23
	v_mul_f32_e32 v65, v61, v23
	v_fma_f32 v66, -v8, v65, v61
	v_fmac_f32_e32 v65, v66, v23
	v_fma_f32 v8, -v8, v65, v61
	v_div_fmas_f32 v8, v8, v23, v65
	v_div_fixup_f32 v4, v8, v5, v4
	ds_write_b32 v2, v4 offset:15360
	s_waitcnt vmcnt(43)
	v_mov_b32_e32 v4, v230
	v_mul_f32_e32 v5, 0xbfb8aa3b, v4
	v_fma_f32 v8, v4, s67, -v5
	v_rndne_f32_e32 v23, v5
	v_fmac_f32_e32 v8, 0xb2a5705f, v4
	v_sub_f32_e32 v5, v5, v23
	v_add_f32_e32 v5, v5, v8
	v_cvt_i32_f32_e32 v23, v23
	v_exp_f32_e32 v5, v5
	v_cmp_nlt_f32_e32 vcc, s68, v4
	v_ldexp_f32 v5, v5, v23
	s_nop 0
	v_cndmask_b32_e32 v5, 0, v5, vcc
	v_cmp_ngt_f32_e32 vcc, s69, v4
	s_nop 1
	v_cndmask_b32_e32 v5, v95, v5, vcc
	v_add_f32_e32 v5, 1.0, v5
	v_div_scale_f32 v8, s[54:55], v5, v5, v4
	v_rcp_f32_e32 v23, v8
	v_div_scale_f32 v61, vcc, v4, v5, v4
	v_fma_f32 v65, -v8, v23, 1.0
	v_fmac_f32_e32 v23, v65, v23
	v_mul_f32_e32 v65, v61, v23
	v_fma_f32 v66, -v8, v65, v61
	v_fmac_f32_e32 v65, v66, v23
	v_fma_f32 v8, -v8, v65, v61
	v_div_fmas_f32 v8, v8, v23, v65
	v_div_fixup_f32 v4, v8, v5, v4
	ds_write_b32 v2, v4 offset:16384
	s_waitcnt vmcnt(42)
	v_mov_b32_e32 v4, v231
	v_mul_f32_e32 v5, 0xbfb8aa3b, v4
	v_fma_f32 v8, v4, s67, -v5
	v_rndne_f32_e32 v23, v5
	v_fmac_f32_e32 v8, 0xb2a5705f, v4
	v_sub_f32_e32 v5, v5, v23
	v_add_f32_e32 v5, v5, v8
	v_cvt_i32_f32_e32 v23, v23
	v_exp_f32_e32 v5, v5
	v_cmp_nlt_f32_e32 vcc, s68, v4
	v_ldexp_f32 v5, v5, v23
	s_nop 0
	v_cndmask_b32_e32 v5, 0, v5, vcc
	v_cmp_ngt_f32_e32 vcc, s69, v4
	s_nop 1
	v_cndmask_b32_e32 v5, v95, v5, vcc
	v_add_f32_e32 v5, 1.0, v5
	v_div_scale_f32 v8, s[54:55], v5, v5, v4
	v_rcp_f32_e32 v23, v8
	v_div_scale_f32 v61, vcc, v4, v5, v4
	v_fma_f32 v65, -v8, v23, 1.0
	v_fmac_f32_e32 v23, v65, v23
	v_mul_f32_e32 v65, v61, v23
	v_fma_f32 v66, -v8, v65, v61
	v_fmac_f32_e32 v65, v66, v23
	v_fma_f32 v8, -v8, v65, v61
	v_div_fmas_f32 v8, v8, v23, v65
	v_div_fixup_f32 v4, v8, v5, v4
	ds_write_b32 v2, v4 offset:17408
	s_waitcnt vmcnt(41)
	v_mov_b32_e32 v4, v232
	v_mul_f32_e32 v5, 0xbfb8aa3b, v4
	v_fma_f32 v8, v4, s67, -v5
	v_rndne_f32_e32 v23, v5
	v_fmac_f32_e32 v8, 0xb2a5705f, v4
	v_sub_f32_e32 v5, v5, v23
	v_add_f32_e32 v5, v5, v8
	v_cvt_i32_f32_e32 v23, v23
	v_exp_f32_e32 v5, v5
	v_cmp_nlt_f32_e32 vcc, s68, v4
	v_ldexp_f32 v5, v5, v23
	s_nop 0
	v_cndmask_b32_e32 v5, 0, v5, vcc
	v_cmp_ngt_f32_e32 vcc, s69, v4
	s_nop 1
	v_cndmask_b32_e32 v5, v95, v5, vcc
	v_add_f32_e32 v5, 1.0, v5
	v_div_scale_f32 v8, s[54:55], v5, v5, v4
	v_rcp_f32_e32 v23, v8
	v_div_scale_f32 v61, vcc, v4, v5, v4
	v_fma_f32 v65, -v8, v23, 1.0
	v_fmac_f32_e32 v23, v65, v23
	v_mul_f32_e32 v65, v61, v23
	v_fma_f32 v66, -v8, v65, v61
	v_fmac_f32_e32 v65, v66, v23
	v_fma_f32 v8, -v8, v65, v61
	v_div_fmas_f32 v8, v8, v23, v65
	v_div_fixup_f32 v4, v8, v5, v4
	ds_write_b32 v2, v4 offset:18432
	s_waitcnt vmcnt(40)
	v_mov_b32_e32 v4, v233
	v_mul_f32_e32 v5, 0xbfb8aa3b, v4
	v_fma_f32 v8, v4, s67, -v5
	v_rndne_f32_e32 v23, v5
	v_fmac_f32_e32 v8, 0xb2a5705f, v4
	v_sub_f32_e32 v5, v5, v23
	v_add_f32_e32 v5, v5, v8
	v_cvt_i32_f32_e32 v23, v23
	v_exp_f32_e32 v5, v5
	v_cmp_nlt_f32_e32 vcc, s68, v4
	v_ldexp_f32 v5, v5, v23
	s_nop 0
	v_cndmask_b32_e32 v5, 0, v5, vcc
	v_cmp_ngt_f32_e32 vcc, s69, v4
	s_nop 1
	v_cndmask_b32_e32 v5, v95, v5, vcc
	v_add_f32_e32 v5, 1.0, v5
	v_div_scale_f32 v8, s[54:55], v5, v5, v4
	v_rcp_f32_e32 v23, v8
	v_div_scale_f32 v61, vcc, v4, v5, v4
	v_fma_f32 v65, -v8, v23, 1.0
	v_fmac_f32_e32 v23, v65, v23
	v_mul_f32_e32 v65, v61, v23
	v_fma_f32 v66, -v8, v65, v61
	v_fmac_f32_e32 v65, v66, v23
	v_fma_f32 v8, -v8, v65, v61
	v_div_fmas_f32 v8, v8, v23, v65
	v_div_fixup_f32 v4, v8, v5, v4
	ds_write_b32 v2, v4 offset:19456
	s_waitcnt vmcnt(39)
	v_mov_b32_e32 v4, v234
	v_mul_f32_e32 v5, 0xbfb8aa3b, v4
	v_fma_f32 v8, v4, s67, -v5
	v_rndne_f32_e32 v23, v5
	v_fmac_f32_e32 v8, 0xb2a5705f, v4
	v_sub_f32_e32 v5, v5, v23
	v_add_f32_e32 v5, v5, v8
	v_cvt_i32_f32_e32 v23, v23
	v_exp_f32_e32 v5, v5
	v_cmp_nlt_f32_e32 vcc, s68, v4
	v_ldexp_f32 v5, v5, v23
	s_nop 0
	v_cndmask_b32_e32 v5, 0, v5, vcc
	v_cmp_ngt_f32_e32 vcc, s69, v4
	s_nop 1
	v_cndmask_b32_e32 v5, v95, v5, vcc
	v_add_f32_e32 v5, 1.0, v5
	v_div_scale_f32 v8, s[54:55], v5, v5, v4
	v_rcp_f32_e32 v23, v8
	v_div_scale_f32 v61, vcc, v4, v5, v4
	v_fma_f32 v65, -v8, v23, 1.0
	v_fmac_f32_e32 v23, v65, v23
	v_mul_f32_e32 v65, v61, v23
	v_fma_f32 v66, -v8, v65, v61
	v_fmac_f32_e32 v65, v66, v23
	v_fma_f32 v8, -v8, v65, v61
	v_div_fmas_f32 v8, v8, v23, v65
	v_div_fixup_f32 v4, v8, v5, v4
	ds_write_b32 v2, v4 offset:20480
	s_waitcnt vmcnt(38)
	v_mov_b32_e32 v4, v235
	v_mul_f32_e32 v5, 0xbfb8aa3b, v4
	v_fma_f32 v8, v4, s67, -v5
	v_rndne_f32_e32 v23, v5
	v_fmac_f32_e32 v8, 0xb2a5705f, v4
	v_sub_f32_e32 v5, v5, v23
	v_add_f32_e32 v5, v5, v8
	v_cvt_i32_f32_e32 v23, v23
	v_exp_f32_e32 v5, v5
	v_cmp_nlt_f32_e32 vcc, s68, v4
	v_ldexp_f32 v5, v5, v23
	s_nop 0
	v_cndmask_b32_e32 v5, 0, v5, vcc
	v_cmp_ngt_f32_e32 vcc, s69, v4
	s_nop 1
	v_cndmask_b32_e32 v5, v95, v5, vcc
	v_add_f32_e32 v5, 1.0, v5
	v_div_scale_f32 v8, s[54:55], v5, v5, v4
	v_rcp_f32_e32 v23, v8
	v_div_scale_f32 v61, vcc, v4, v5, v4
	v_fma_f32 v65, -v8, v23, 1.0
	v_fmac_f32_e32 v23, v65, v23
	v_mul_f32_e32 v65, v61, v23
	v_fma_f32 v66, -v8, v65, v61
	v_fmac_f32_e32 v65, v66, v23
	v_fma_f32 v8, -v8, v65, v61
	v_div_fmas_f32 v8, v8, v23, v65
	v_div_fixup_f32 v4, v8, v5, v4
	ds_write_b32 v2, v4 offset:21504
	s_waitcnt vmcnt(37)
	v_mov_b32_e32 v4, v236
	v_mul_f32_e32 v5, 0xbfb8aa3b, v4
	v_fma_f32 v8, v4, s67, -v5
	v_rndne_f32_e32 v23, v5
	v_fmac_f32_e32 v8, 0xb2a5705f, v4
	v_sub_f32_e32 v5, v5, v23
	v_add_f32_e32 v5, v5, v8
	v_cvt_i32_f32_e32 v23, v23
	v_exp_f32_e32 v5, v5
	v_cmp_nlt_f32_e32 vcc, s68, v4
	v_ldexp_f32 v5, v5, v23
	s_nop 0
	v_cndmask_b32_e32 v5, 0, v5, vcc
	v_cmp_ngt_f32_e32 vcc, s69, v4
	s_nop 1
	v_cndmask_b32_e32 v5, v95, v5, vcc
	v_add_f32_e32 v5, 1.0, v5
	v_div_scale_f32 v8, s[54:55], v5, v5, v4
	v_rcp_f32_e32 v23, v8
	v_div_scale_f32 v61, vcc, v4, v5, v4
	v_fma_f32 v65, -v8, v23, 1.0
	v_fmac_f32_e32 v23, v65, v23
	v_mul_f32_e32 v65, v61, v23
	v_fma_f32 v66, -v8, v65, v61
	v_fmac_f32_e32 v65, v66, v23
	v_fma_f32 v8, -v8, v65, v61
	v_div_fmas_f32 v8, v8, v23, v65
	v_div_fixup_f32 v4, v8, v5, v4
	ds_write_b32 v2, v4 offset:22528
	s_waitcnt vmcnt(36)
	v_mov_b32_e32 v4, v237
	v_mul_f32_e32 v5, 0xbfb8aa3b, v4
	v_fma_f32 v8, v4, s67, -v5
	v_rndne_f32_e32 v23, v5
	v_fmac_f32_e32 v8, 0xb2a5705f, v4
	v_sub_f32_e32 v5, v5, v23
	v_add_f32_e32 v5, v5, v8
	v_cvt_i32_f32_e32 v23, v23
	v_exp_f32_e32 v5, v5
	v_cmp_nlt_f32_e32 vcc, s68, v4
	v_ldexp_f32 v5, v5, v23
	s_nop 0
	v_cndmask_b32_e32 v5, 0, v5, vcc
	v_cmp_ngt_f32_e32 vcc, s69, v4
	s_nop 1
	v_cndmask_b32_e32 v5, v95, v5, vcc
	v_add_f32_e32 v5, 1.0, v5
	v_div_scale_f32 v8, s[54:55], v5, v5, v4
	v_rcp_f32_e32 v23, v8
	v_div_scale_f32 v61, vcc, v4, v5, v4
	v_fma_f32 v65, -v8, v23, 1.0
	v_fmac_f32_e32 v23, v65, v23
	v_mul_f32_e32 v65, v61, v23
	v_fma_f32 v66, -v8, v65, v61
	v_fmac_f32_e32 v65, v66, v23
	v_fma_f32 v8, -v8, v65, v61
	v_div_fmas_f32 v8, v8, v23, v65
	v_div_fixup_f32 v4, v8, v5, v4
	ds_write_b32 v2, v4 offset:23552
	s_waitcnt vmcnt(35)
	v_mov_b32_e32 v4, v239
	v_mul_f32_e32 v5, 0xbfb8aa3b, v4
	v_fma_f32 v8, v4, s67, -v5
	v_rndne_f32_e32 v23, v5
	v_fmac_f32_e32 v8, 0xb2a5705f, v4
	v_sub_f32_e32 v5, v5, v23
	v_add_f32_e32 v5, v5, v8
	v_cvt_i32_f32_e32 v23, v23
	v_exp_f32_e32 v5, v5
	v_cmp_nlt_f32_e32 vcc, s68, v4
	v_ldexp_f32 v5, v5, v23
	s_nop 0
	v_cndmask_b32_e32 v5, 0, v5, vcc
	v_cmp_ngt_f32_e32 vcc, s69, v4
	s_nop 1
	v_cndmask_b32_e32 v5, v95, v5, vcc
	v_add_f32_e32 v5, 1.0, v5
	v_div_scale_f32 v8, s[54:55], v5, v5, v4
	v_rcp_f32_e32 v23, v8
	v_div_scale_f32 v61, vcc, v4, v5, v4
	v_fma_f32 v65, -v8, v23, 1.0
	v_fmac_f32_e32 v23, v65, v23
	v_mul_f32_e32 v65, v61, v23
	v_fma_f32 v66, -v8, v65, v61
	v_fmac_f32_e32 v65, v66, v23
	v_fma_f32 v8, -v8, v65, v61
	v_div_fmas_f32 v8, v8, v23, v65
	v_div_fixup_f32 v4, v8, v5, v4
	ds_write_b32 v2, v4 offset:24576
	s_waitcnt vmcnt(34)
	v_mov_b32_e32 v4, v240
	v_mul_f32_e32 v5, 0xbfb8aa3b, v4
	v_fma_f32 v8, v4, s67, -v5
	v_rndne_f32_e32 v23, v5
	v_fmac_f32_e32 v8, 0xb2a5705f, v4
	v_sub_f32_e32 v5, v5, v23
	v_add_f32_e32 v5, v5, v8
	v_cvt_i32_f32_e32 v23, v23
	v_exp_f32_e32 v5, v5
	v_cmp_nlt_f32_e32 vcc, s68, v4
	v_ldexp_f32 v5, v5, v23
	s_nop 0
	v_cndmask_b32_e32 v5, 0, v5, vcc
	v_cmp_ngt_f32_e32 vcc, s69, v4
	s_nop 1
	v_cndmask_b32_e32 v5, v95, v5, vcc
	v_add_f32_e32 v5, 1.0, v5
	v_div_scale_f32 v8, s[54:55], v5, v5, v4
	v_rcp_f32_e32 v23, v8
	v_div_scale_f32 v61, vcc, v4, v5, v4
	v_fma_f32 v65, -v8, v23, 1.0
	v_fmac_f32_e32 v23, v65, v23
	v_mul_f32_e32 v65, v61, v23
	v_fma_f32 v66, -v8, v65, v61
	v_fmac_f32_e32 v65, v66, v23
	v_fma_f32 v8, -v8, v65, v61
	v_div_fmas_f32 v8, v8, v23, v65
	v_div_fixup_f32 v4, v8, v5, v4
	ds_write_b32 v2, v4 offset:25600
	s_waitcnt vmcnt(33)
	v_mov_b32_e32 v4, v241
	v_mul_f32_e32 v5, 0xbfb8aa3b, v4
	v_fma_f32 v8, v4, s67, -v5
	v_rndne_f32_e32 v23, v5
	v_fmac_f32_e32 v8, 0xb2a5705f, v4
	v_sub_f32_e32 v5, v5, v23
	v_add_f32_e32 v5, v5, v8
	v_cvt_i32_f32_e32 v23, v23
	v_exp_f32_e32 v5, v5
	v_cmp_nlt_f32_e32 vcc, s68, v4
	v_ldexp_f32 v5, v5, v23
	s_nop 0
	v_cndmask_b32_e32 v5, 0, v5, vcc
	v_cmp_ngt_f32_e32 vcc, s69, v4
	s_nop 1
	v_cndmask_b32_e32 v5, v95, v5, vcc
	v_add_f32_e32 v5, 1.0, v5
	v_div_scale_f32 v8, s[54:55], v5, v5, v4
	v_rcp_f32_e32 v23, v8
	v_div_scale_f32 v61, vcc, v4, v5, v4
	v_fma_f32 v65, -v8, v23, 1.0
	v_fmac_f32_e32 v23, v65, v23
	v_mul_f32_e32 v65, v61, v23
	v_fma_f32 v66, -v8, v65, v61
	v_fmac_f32_e32 v65, v66, v23
	v_fma_f32 v8, -v8, v65, v61
	v_div_fmas_f32 v8, v8, v23, v65
	v_div_fixup_f32 v4, v8, v5, v4
	ds_write_b32 v2, v4 offset:26624
	s_waitcnt vmcnt(32)
	v_mov_b32_e32 v4, v242
	v_mul_f32_e32 v5, 0xbfb8aa3b, v4
	v_fma_f32 v8, v4, s67, -v5
	v_rndne_f32_e32 v23, v5
	v_fmac_f32_e32 v8, 0xb2a5705f, v4
	v_sub_f32_e32 v5, v5, v23
	v_add_f32_e32 v5, v5, v8
	v_cvt_i32_f32_e32 v23, v23
	v_exp_f32_e32 v5, v5
	v_cmp_nlt_f32_e32 vcc, s68, v4
	v_ldexp_f32 v5, v5, v23
	s_nop 0
	v_cndmask_b32_e32 v5, 0, v5, vcc
	v_cmp_ngt_f32_e32 vcc, s69, v4
	s_nop 1
	v_cndmask_b32_e32 v5, v95, v5, vcc
	v_add_f32_e32 v5, 1.0, v5
	v_div_scale_f32 v8, s[54:55], v5, v5, v4
	v_rcp_f32_e32 v23, v8
	v_div_scale_f32 v61, vcc, v4, v5, v4
	v_fma_f32 v65, -v8, v23, 1.0
	v_fmac_f32_e32 v23, v65, v23
	v_mul_f32_e32 v65, v61, v23
	v_fma_f32 v66, -v8, v65, v61
	v_fmac_f32_e32 v65, v66, v23
	v_fma_f32 v8, -v8, v65, v61
	v_div_fmas_f32 v8, v8, v23, v65
	v_div_fixup_f32 v4, v8, v5, v4
	ds_write_b32 v2, v4 offset:27648
	s_waitcnt vmcnt(31)
	v_mov_b32_e32 v4, v243
	v_mul_f32_e32 v5, 0xbfb8aa3b, v4
	v_fma_f32 v8, v4, s67, -v5
	v_rndne_f32_e32 v23, v5
	v_fmac_f32_e32 v8, 0xb2a5705f, v4
	v_sub_f32_e32 v5, v5, v23
	v_add_f32_e32 v5, v5, v8
	v_cvt_i32_f32_e32 v23, v23
	v_exp_f32_e32 v5, v5
	v_cmp_nlt_f32_e32 vcc, s68, v4
	v_ldexp_f32 v5, v5, v23
	s_nop 0
	v_cndmask_b32_e32 v5, 0, v5, vcc
	v_cmp_ngt_f32_e32 vcc, s69, v4
	s_nop 1
	v_cndmask_b32_e32 v5, v95, v5, vcc
	v_add_f32_e32 v5, 1.0, v5
	v_div_scale_f32 v8, s[54:55], v5, v5, v4
	v_rcp_f32_e32 v23, v8
	v_div_scale_f32 v61, vcc, v4, v5, v4
	v_fma_f32 v65, -v8, v23, 1.0
	v_fmac_f32_e32 v23, v65, v23
	v_mul_f32_e32 v65, v61, v23
	v_fma_f32 v66, -v8, v65, v61
	v_fmac_f32_e32 v65, v66, v23
	v_fma_f32 v8, -v8, v65, v61
	v_div_fmas_f32 v8, v8, v23, v65
	v_div_fixup_f32 v4, v8, v5, v4
	ds_write_b32 v2, v4 offset:28672
	s_waitcnt vmcnt(30)
	v_mov_b32_e32 v4, v244
	v_mul_f32_e32 v5, 0xbfb8aa3b, v4
	v_fma_f32 v8, v4, s67, -v5
	v_rndne_f32_e32 v23, v5
	v_fmac_f32_e32 v8, 0xb2a5705f, v4
	v_sub_f32_e32 v5, v5, v23
	v_add_f32_e32 v5, v5, v8
	v_cvt_i32_f32_e32 v23, v23
	v_exp_f32_e32 v5, v5
	v_cmp_nlt_f32_e32 vcc, s68, v4
	v_ldexp_f32 v5, v5, v23
	s_nop 0
	v_cndmask_b32_e32 v5, 0, v5, vcc
	v_cmp_ngt_f32_e32 vcc, s69, v4
	s_nop 1
	v_cndmask_b32_e32 v5, v95, v5, vcc
	v_add_f32_e32 v5, 1.0, v5
	v_div_scale_f32 v8, s[54:55], v5, v5, v4
	v_rcp_f32_e32 v23, v8
	v_div_scale_f32 v61, vcc, v4, v5, v4
	v_fma_f32 v65, -v8, v23, 1.0
	v_fmac_f32_e32 v23, v65, v23
	v_mul_f32_e32 v65, v61, v23
	v_fma_f32 v66, -v8, v65, v61
	v_fmac_f32_e32 v65, v66, v23
	v_fma_f32 v8, -v8, v65, v61
	v_div_fmas_f32 v8, v8, v23, v65
	v_div_fixup_f32 v4, v8, v5, v4
	ds_write_b32 v2, v4 offset:29696
	s_waitcnt vmcnt(29)
	v_mov_b32_e32 v4, v245
	v_mul_f32_e32 v5, 0xbfb8aa3b, v4
	v_fma_f32 v8, v4, s67, -v5
	v_rndne_f32_e32 v23, v5
	v_fmac_f32_e32 v8, 0xb2a5705f, v4
	v_sub_f32_e32 v5, v5, v23
	v_add_f32_e32 v5, v5, v8
	v_cvt_i32_f32_e32 v23, v23
	v_exp_f32_e32 v5, v5
	v_cmp_nlt_f32_e32 vcc, s68, v4
	v_ldexp_f32 v5, v5, v23
	s_nop 0
	v_cndmask_b32_e32 v5, 0, v5, vcc
	v_cmp_ngt_f32_e32 vcc, s69, v4
	s_nop 1
	v_cndmask_b32_e32 v5, v95, v5, vcc
	v_add_f32_e32 v5, 1.0, v5
	v_div_scale_f32 v8, s[54:55], v5, v5, v4
	v_rcp_f32_e32 v23, v8
	v_div_scale_f32 v61, vcc, v4, v5, v4
	v_fma_f32 v65, -v8, v23, 1.0
	v_fmac_f32_e32 v23, v65, v23
	v_mul_f32_e32 v65, v61, v23
	v_fma_f32 v66, -v8, v65, v61
	v_fmac_f32_e32 v65, v66, v23
	v_fma_f32 v8, -v8, v65, v61
	v_div_fmas_f32 v8, v8, v23, v65
	v_div_fixup_f32 v4, v8, v5, v4
	ds_write_b32 v2, v4 offset:30720
	s_waitcnt vmcnt(28)
	v_mov_b32_e32 v4, v246
	v_mul_f32_e32 v5, 0xbfb8aa3b, v4
	v_fma_f32 v8, v4, s67, -v5
	v_rndne_f32_e32 v23, v5
	v_fmac_f32_e32 v8, 0xb2a5705f, v4
	v_sub_f32_e32 v5, v5, v23
	v_add_f32_e32 v5, v5, v8
	v_cvt_i32_f32_e32 v23, v23
	v_exp_f32_e32 v5, v5
	v_cmp_nlt_f32_e32 vcc, s68, v4
	v_ldexp_f32 v5, v5, v23
	s_nop 0
	v_cndmask_b32_e32 v5, 0, v5, vcc
	v_cmp_ngt_f32_e32 vcc, s69, v4
	s_nop 1
	v_cndmask_b32_e32 v5, v95, v5, vcc
	v_add_f32_e32 v5, 1.0, v5
	v_div_scale_f32 v8, s[54:55], v5, v5, v4
	v_rcp_f32_e32 v23, v8
	v_div_scale_f32 v61, vcc, v4, v5, v4
	v_fma_f32 v65, -v8, v23, 1.0
	v_fmac_f32_e32 v23, v65, v23
	v_mul_f32_e32 v65, v61, v23
	v_fma_f32 v66, -v8, v65, v61
	v_fmac_f32_e32 v65, v66, v23
	v_fma_f32 v8, -v8, v65, v61
	v_div_fmas_f32 v8, v8, v23, v65
	v_div_fixup_f32 v4, v8, v5, v4
	ds_write_b32 v2, v4 offset:31744
	s_waitcnt vmcnt(27)
	v_mov_b32_e32 v4, v247
	v_mul_f32_e32 v5, 0xbfb8aa3b, v4
	v_fma_f32 v8, v4, s67, -v5
	v_rndne_f32_e32 v23, v5
	v_fmac_f32_e32 v8, 0xb2a5705f, v4
	v_sub_f32_e32 v5, v5, v23
	v_add_f32_e32 v5, v5, v8
	v_cvt_i32_f32_e32 v23, v23
	v_exp_f32_e32 v5, v5
	v_cmp_nlt_f32_e32 vcc, s68, v4
	v_ldexp_f32 v5, v5, v23
	s_nop 0
	v_cndmask_b32_e32 v5, 0, v5, vcc
	v_cmp_ngt_f32_e32 vcc, s69, v4
	s_nop 1
	v_cndmask_b32_e32 v5, v95, v5, vcc
	v_add_f32_e32 v5, 1.0, v5
	v_div_scale_f32 v8, s[54:55], v5, v5, v4
	v_rcp_f32_e32 v23, v8
	v_div_scale_f32 v61, vcc, v4, v5, v4
	v_fma_f32 v65, -v8, v23, 1.0
	v_fmac_f32_e32 v23, v65, v23
	v_mul_f32_e32 v65, v61, v23
	v_fma_f32 v66, -v8, v65, v61
	v_fmac_f32_e32 v65, v66, v23
	v_fma_f32 v8, -v8, v65, v61
	v_div_fmas_f32 v8, v8, v23, v65
	v_div_fixup_f32 v4, v8, v5, v4
	ds_write_b32 v2, v4 offset:32768
	s_waitcnt vmcnt(26)
	v_mov_b32_e32 v4, v248
	v_mul_f32_e32 v5, 0xbfb8aa3b, v4
	v_fma_f32 v8, v4, s67, -v5
	v_rndne_f32_e32 v23, v5
	v_fmac_f32_e32 v8, 0xb2a5705f, v4
	v_sub_f32_e32 v5, v5, v23
	v_add_f32_e32 v5, v5, v8
	v_cvt_i32_f32_e32 v23, v23
	v_exp_f32_e32 v5, v5
	v_cmp_nlt_f32_e32 vcc, s68, v4
	v_ldexp_f32 v5, v5, v23
	s_nop 0
	v_cndmask_b32_e32 v5, 0, v5, vcc
	v_cmp_ngt_f32_e32 vcc, s69, v4
	s_nop 1
	v_cndmask_b32_e32 v5, v95, v5, vcc
	v_add_f32_e32 v5, 1.0, v5
	v_div_scale_f32 v8, s[54:55], v5, v5, v4
	v_rcp_f32_e32 v23, v8
	v_div_scale_f32 v61, vcc, v4, v5, v4
	v_fma_f32 v65, -v8, v23, 1.0
	v_fmac_f32_e32 v23, v65, v23
	v_mul_f32_e32 v65, v61, v23
	v_fma_f32 v66, -v8, v65, v61
	v_fmac_f32_e32 v65, v66, v23
	v_fma_f32 v8, -v8, v65, v61
	v_div_fmas_f32 v8, v8, v23, v65
	v_div_fixup_f32 v4, v8, v5, v4
	ds_write_b32 v2, v4 offset:33792
	s_waitcnt vmcnt(25)
	v_mov_b32_e32 v4, v249
	v_mul_f32_e32 v5, 0xbfb8aa3b, v4
	v_fma_f32 v8, v4, s67, -v5
	v_rndne_f32_e32 v23, v5
	v_fmac_f32_e32 v8, 0xb2a5705f, v4
	v_sub_f32_e32 v5, v5, v23
	v_add_f32_e32 v5, v5, v8
	v_cvt_i32_f32_e32 v23, v23
	v_exp_f32_e32 v5, v5
	v_cmp_nlt_f32_e32 vcc, s68, v4
	v_ldexp_f32 v5, v5, v23
	s_nop 0
	v_cndmask_b32_e32 v5, 0, v5, vcc
	v_cmp_ngt_f32_e32 vcc, s69, v4
	s_nop 1
	v_cndmask_b32_e32 v5, v95, v5, vcc
	v_add_f32_e32 v5, 1.0, v5
	v_div_scale_f32 v8, s[54:55], v5, v5, v4
	v_rcp_f32_e32 v23, v8
	v_div_scale_f32 v61, vcc, v4, v5, v4
	v_fma_f32 v65, -v8, v23, 1.0
	v_fmac_f32_e32 v23, v65, v23
	v_mul_f32_e32 v65, v61, v23
	v_fma_f32 v66, -v8, v65, v61
	v_fmac_f32_e32 v65, v66, v23
	v_fma_f32 v8, -v8, v65, v61
	v_div_fmas_f32 v8, v8, v23, v65
	v_div_fixup_f32 v4, v8, v5, v4
	ds_write_b32 v2, v4 offset:34816
	s_waitcnt vmcnt(24)
	v_mov_b32_e32 v4, v250
	v_mul_f32_e32 v5, 0xbfb8aa3b, v4
	v_fma_f32 v8, v4, s67, -v5
	v_rndne_f32_e32 v23, v5
	v_fmac_f32_e32 v8, 0xb2a5705f, v4
	v_sub_f32_e32 v5, v5, v23
	v_add_f32_e32 v5, v5, v8
	v_cvt_i32_f32_e32 v23, v23
	v_exp_f32_e32 v5, v5
	v_cmp_nlt_f32_e32 vcc, s68, v4
	v_ldexp_f32 v5, v5, v23
	s_nop 0
	v_cndmask_b32_e32 v5, 0, v5, vcc
	v_cmp_ngt_f32_e32 vcc, s69, v4
	s_nop 1
	v_cndmask_b32_e32 v5, v95, v5, vcc
	v_add_f32_e32 v5, 1.0, v5
	v_div_scale_f32 v8, s[54:55], v5, v5, v4
	v_rcp_f32_e32 v23, v8
	v_div_scale_f32 v61, vcc, v4, v5, v4
	v_fma_f32 v65, -v8, v23, 1.0
	v_fmac_f32_e32 v23, v65, v23
	v_mul_f32_e32 v65, v61, v23
	v_fma_f32 v66, -v8, v65, v61
	v_fmac_f32_e32 v65, v66, v23
	v_fma_f32 v8, -v8, v65, v61
	v_div_fmas_f32 v8, v8, v23, v65
	v_div_fixup_f32 v4, v8, v5, v4
	ds_write_b32 v2, v4 offset:35840
	s_or_b64 exec, exec, s[52:53]
	v_mov_b32_e32 v2, s72
	s_waitcnt lgkmcnt(0)
	s_barrier
	ds_read_b64 v[2:3], v2
	v_mov_b32_e32 v61, v9
	v_mov_b32_e32 v4, 0
	s_mov_b64 s[52:53], 0
	v_mov_b32_e32 v8, v81
	s_waitcnt lgkmcnt(0)
	v_add_co_u32_e32 v2, vcc, v2, v10
	v_addc_co_u32_e32 v3, vcc, v3, v11, vcc
	v_lshl_add_u64 v[2:3], v[60:61], 2, v[2:3]
	v_mov_b32_e32 v5, v4
	v_mov_b32_e32 v68, v4
	v_mov_b32_e32 v69, v4
	v_mov_b32_e32 v70, v4
	v_mov_b32_e32 v71, v4
	v_mov_b32_e32 v72, v4
	v_mov_b32_e32 v73, v4
	v_mov_b32_e32 v23, v4
	v_mov_b32_e32 v196, 0
	v_mov_b32_e32 v197, 0
	v_mov_b32_e32 v198, 0
	v_mov_b32_e32 v199, 0
	v_mov_b32_e32 v200, 0
	v_mov_b32_e32 v201, 0
	v_mov_b32_e32 v202, 0
	v_mov_b32_e32 v203, 0
	v_mov_b32_e32 v204, 0
	v_mov_b32_e32 v205, 0
	v_mov_b32_e32 v206, 0
	v_mov_b32_e32 v207, 0
	v_mov_b32_e32 v208, 0
	v_mov_b32_e32 v209, 0
	v_mov_b32_e32 v210, 0
	v_mov_b32_e32 v211, 0
	v_mov_b32_e32 v212, 0
	v_mov_b32_e32 v213, 0
	global_load_dword v174, v[194:195], off nt
	v_add_co_u32_e32 v194, vcc, 0x6000, v194
	v_addc_co_u32_e32 v195, vcc, 0, v195, vcc
	global_load_dword v175, v[194:195], off nt
	v_add_co_u32_e32 v194, vcc, 0x6000, v194
	v_addc_co_u32_e32 v195, vcc, 0, v195, vcc
	global_load_dword v176, v[194:195], off nt
	v_add_co_u32_e32 v194, vcc, 0x6000, v194
	v_addc_co_u32_e32 v195, vcc, 0, v195, vcc
	global_load_dword v177, v[194:195], off nt
	v_add_co_u32_e32 v194, vcc, 0x6000, v194
	v_addc_co_u32_e32 v195, vcc, 0, v195, vcc
	global_load_dword v178, v[194:195], off nt
	v_add_co_u32_e32 v194, vcc, 0x6000, v194
	v_addc_co_u32_e32 v195, vcc, 0, v195, vcc
	global_load_dword v179, v[194:195], off nt
	v_add_co_u32_e32 v194, vcc, 0x6000, v194
	v_addc_co_u32_e32 v195, vcc, 0, v195, vcc
	global_load_dword v180, v[194:195], off nt
	v_add_co_u32_e32 v194, vcc, 0x6000, v194
	v_addc_co_u32_e32 v195, vcc, 0, v195, vcc
	global_load_dword v181, v[194:195], off nt
	v_add_co_u32_e32 v194, vcc, 0x6000, v194
	v_addc_co_u32_e32 v195, vcc, 0, v195, vcc
	global_load_dword v182, v[194:195], off nt
	v_add_co_u32_e32 v194, vcc, 0x6000, v194
	v_addc_co_u32_e32 v195, vcc, 0, v195, vcc
	global_load_dword v183, v[194:195], off nt
	v_add_co_u32_e32 v194, vcc, 0x6000, v194
	v_addc_co_u32_e32 v195, vcc, 0, v195, vcc
	global_load_dword v184, v[194:195], off nt
	v_add_co_u32_e32 v194, vcc, 0x6000, v194
	v_addc_co_u32_e32 v195, vcc, 0, v195, vcc
	global_load_dword v185, v[194:195], off nt
	v_add_co_u32_e32 v194, vcc, 0x6000, v194
	v_addc_co_u32_e32 v195, vcc, 0, v195, vcc
	global_load_dword v186, v[194:195], off nt
	v_add_co_u32_e32 v194, vcc, 0x6000, v194
	v_addc_co_u32_e32 v195, vcc, 0, v195, vcc
	global_load_dword v187, v[194:195], off nt
	v_add_co_u32_e32 v194, vcc, 0x6000, v194
	v_addc_co_u32_e32 v195, vcc, 0, v195, vcc
	global_load_dword v188, v[194:195], off nt
	v_add_co_u32_e32 v194, vcc, 0x6000, v194
	v_addc_co_u32_e32 v195, vcc, 0, v195, vcc
	global_load_dword v189, v[194:195], off nt
	v_add_co_u32_e32 v194, vcc, 0x6000, v194
	v_addc_co_u32_e32 v195, vcc, 0, v195, vcc
	global_load_dword v190, v[194:195], off nt
	v_add_co_u32_e32 v194, vcc, 0x6000, v194
	v_addc_co_u32_e32 v195, vcc, 0, v195, vcc
	global_load_dword v191, v[194:195], off nt
	v_add_co_u32_e32 v194, vcc, 0x6000, v194
	v_addc_co_u32_e32 v195, vcc, 0, v195, vcc
	global_load_dword v192, v[194:195], off nt
	v_add_co_u32_e32 v194, vcc, 0x6000, v194
	v_addc_co_u32_e32 v195, vcc, 0, v195, vcc
	global_load_dword v193, v[194:195], off nt
	v_add_co_u32_e32 v194, vcc, 0x6000, v194
	v_addc_co_u32_e32 v195, vcc, 0, v195, vcc
	ds_read_b128 v[98:101], v8 offset:4096
	ds_read_b128 v[102:105], v8 offset:8192
	ds_read_b128 v[106:109], v8 offset:12288
	ds_read_b128 v[110:113], v8 offset:16384
	ds_read_b128 v[114:117], v8 offset:20480
	ds_read_b128 v[118:121], v8 offset:24576
	ds_read_b128 v[122:125], v8 offset:28672
	ds_read_b128 v[126:129], v8
	ds_read_b128 v[134:137], v8 offset:32768
	v_add_u32_e32 v8, 16, v8
	s_waitcnt vmcnt(40) lgkmcnt(0)
	v_pk_fma_f32 v[196:197], v[150:151], v[126:127], v[196:197]
	v_pk_fma_f32 v[198:199], v[150:151], v[98:99], v[198:199]
	v_pk_fma_f32 v[200:201], v[150:151], v[102:103], v[200:201]
	v_pk_fma_f32 v[202:203], v[150:151], v[106:107], v[202:203]
	v_pk_fma_f32 v[204:205], v[150:151], v[110:111], v[204:205]
	v_pk_fma_f32 v[206:207], v[150:151], v[114:115], v[206:207]
	v_pk_fma_f32 v[208:209], v[150:151], v[118:119], v[208:209]
	v_pk_fma_f32 v[210:211], v[150:151], v[122:123], v[210:211]
	v_pk_fma_f32 v[212:213], v[150:151], v[134:135], v[212:213]
	v_pk_fma_f32 v[196:197], v[152:153], v[128:129], v[196:197]
	v_pk_fma_f32 v[198:199], v[152:153], v[100:101], v[198:199]
	v_pk_fma_f32 v[200:201], v[152:153], v[104:105], v[200:201]
	v_pk_fma_f32 v[202:203], v[152:153], v[108:109], v[202:203]
	v_pk_fma_f32 v[204:205], v[152:153], v[112:113], v[204:205]
	v_pk_fma_f32 v[206:207], v[152:153], v[116:117], v[206:207]
	v_pk_fma_f32 v[208:209], v[152:153], v[120:121], v[208:209]
	v_pk_fma_f32 v[210:211], v[152:153], v[124:125], v[210:211]
	v_pk_fma_f32 v[212:213], v[152:153], v[136:137], v[212:213]
	global_load_dword v150, v[194:195], off nt
	v_add_co_u32_e32 v194, vcc, 0x6000, v194
	v_addc_co_u32_e32 v195, vcc, 0, v195, vcc
	global_load_dword v151, v[194:195], off nt
	v_add_co_u32_e32 v194, vcc, 0x6000, v194
	v_addc_co_u32_e32 v195, vcc, 0, v195, vcc
	global_load_dword v152, v[194:195], off nt
	v_add_co_u32_e32 v194, vcc, 0x6000, v194
	v_addc_co_u32_e32 v195, vcc, 0, v195, vcc
	global_load_dword v153, v[194:195], off nt
	v_add_co_u32_e32 v194, vcc, 0x6000, v194
	v_addc_co_u32_e32 v195, vcc, 0, v195, vcc
	ds_read_b128 v[98:101], v8 offset:4096
	ds_read_b128 v[102:105], v8 offset:8192
	ds_read_b128 v[106:109], v8 offset:12288
	ds_read_b128 v[110:113], v8 offset:16384
	ds_read_b128 v[114:117], v8 offset:20480
	ds_read_b128 v[118:121], v8 offset:24576
	ds_read_b128 v[122:125], v8 offset:28672
	ds_read_b128 v[126:129], v8
	ds_read_b128 v[134:137], v8 offset:32768
	v_add_u32_e32 v8, 16, v8
	s_waitcnt vmcnt(40) lgkmcnt(0)
	v_pk_fma_f32 v[196:197], v[154:155], v[126:127], v[196:197]
	v_pk_fma_f32 v[198:199], v[154:155], v[98:99], v[198:199]
	v_pk_fma_f32 v[200:201], v[154:155], v[102:103], v[200:201]
	v_pk_fma_f32 v[202:203], v[154:155], v[106:107], v[202:203]
	v_pk_fma_f32 v[204:205], v[154:155], v[110:111], v[204:205]
	v_pk_fma_f32 v[206:207], v[154:155], v[114:115], v[206:207]
	v_pk_fma_f32 v[208:209], v[154:155], v[118:119], v[208:209]
	v_pk_fma_f32 v[210:211], v[154:155], v[122:123], v[210:211]
	v_pk_fma_f32 v[212:213], v[154:155], v[134:135], v[212:213]
	v_pk_fma_f32 v[196:197], v[156:157], v[128:129], v[196:197]
	v_pk_fma_f32 v[198:199], v[156:157], v[100:101], v[198:199]
	v_pk_fma_f32 v[200:201], v[156:157], v[104:105], v[200:201]
	v_pk_fma_f32 v[202:203], v[156:157], v[108:109], v[202:203]
	v_pk_fma_f32 v[204:205], v[156:157], v[112:113], v[204:205]
	v_pk_fma_f32 v[206:207], v[156:157], v[116:117], v[206:207]
	v_pk_fma_f32 v[208:209], v[156:157], v[120:121], v[208:209]
	v_pk_fma_f32 v[210:211], v[156:157], v[124:125], v[210:211]
	v_pk_fma_f32 v[212:213], v[156:157], v[136:137], v[212:213]
	global_load_dword v154, v[194:195], off nt
	v_add_co_u32_e32 v194, vcc, 0x6000, v194
	v_addc_co_u32_e32 v195, vcc, 0, v195, vcc
	global_load_dword v155, v[194:195], off nt
	v_add_co_u32_e32 v194, vcc, 0x6000, v194
	v_addc_co_u32_e32 v195, vcc, 0, v195, vcc
	global_load_dword v156, v[194:195], off nt
	v_add_co_u32_e32 v194, vcc, 0x6000, v194
	v_addc_co_u32_e32 v195, vcc, 0, v195, vcc
	global_load_dword v157, v[194:195], off nt
	v_add_co_u32_e32 v194, vcc, 0x6000, v194
	v_addc_co_u32_e32 v195, vcc, 0, v195, vcc
	ds_read_b128 v[98:101], v8 offset:4096
	ds_read_b128 v[102:105], v8 offset:8192
	ds_read_b128 v[106:109], v8 offset:12288
	ds_read_b128 v[110:113], v8 offset:16384
	ds_read_b128 v[114:117], v8 offset:20480
	ds_read_b128 v[118:121], v8 offset:24576
	ds_read_b128 v[122:125], v8 offset:28672
	ds_read_b128 v[126:129], v8
	ds_read_b128 v[134:137], v8 offset:32768
	v_add_u32_e32 v8, 16, v8
	s_waitcnt vmcnt(40) lgkmcnt(0)
	v_pk_fma_f32 v[196:197], v[158:159], v[126:127], v[196:197]
	v_pk_fma_f32 v[198:199], v[158:159], v[98:99], v[198:199]
	v_pk_fma_f32 v[200:201], v[158:159], v[102:103], v[200:201]
	v_pk_fma_f32 v[202:203], v[158:159], v[106:107], v[202:203]
	v_pk_fma_f32 v[204:205], v[158:159], v[110:111], v[204:205]
	v_pk_fma_f32 v[206:207], v[158:159], v[114:115], v[206:207]
	v_pk_fma_f32 v[208:209], v[158:159], v[118:119], v[208:209]
	v_pk_fma_f32 v[210:211], v[158:159], v[122:123], v[210:211]
	v_pk_fma_f32 v[212:213], v[158:159], v[134:135], v[212:213]
	v_pk_fma_f32 v[196:197], v[160:161], v[128:129], v[196:197]
	v_pk_fma_f32 v[198:199], v[160:161], v[100:101], v[198:199]
	v_pk_fma_f32 v[200:201], v[160:161], v[104:105], v[200:201]
	v_pk_fma_f32 v[202:203], v[160:161], v[108:109], v[202:203]
	v_pk_fma_f32 v[204:205], v[160:161], v[112:113], v[204:205]
	v_pk_fma_f32 v[206:207], v[160:161], v[116:117], v[206:207]
	v_pk_fma_f32 v[208:209], v[160:161], v[120:121], v[208:209]
	v_pk_fma_f32 v[210:211], v[160:161], v[124:125], v[210:211]
	v_pk_fma_f32 v[212:213], v[160:161], v[136:137], v[212:213]
	global_load_dword v158, v[194:195], off nt
	v_add_co_u32_e32 v194, vcc, 0x6000, v194
	v_addc_co_u32_e32 v195, vcc, 0, v195, vcc
	global_load_dword v159, v[194:195], off nt
	v_add_co_u32_e32 v194, vcc, 0x6000, v194
	v_addc_co_u32_e32 v195, vcc, 0, v195, vcc
	global_load_dword v160, v[194:195], off nt
	v_add_co_u32_e32 v194, vcc, 0x6000, v194
	v_addc_co_u32_e32 v195, vcc, 0, v195, vcc
	global_load_dword v161, v[194:195], off nt
	v_add_co_u32_e32 v194, vcc, 0x6000, v194
	v_addc_co_u32_e32 v195, vcc, 0, v195, vcc
	ds_read_b128 v[98:101], v8 offset:4096
	ds_read_b128 v[102:105], v8 offset:8192
	ds_read_b128 v[106:109], v8 offset:12288
	ds_read_b128 v[110:113], v8 offset:16384
	ds_read_b128 v[114:117], v8 offset:20480
	ds_read_b128 v[118:121], v8 offset:24576
	ds_read_b128 v[122:125], v8 offset:28672
	ds_read_b128 v[126:129], v8
	ds_read_b128 v[134:137], v8 offset:32768
	v_add_u32_e32 v8, 16, v8
	s_waitcnt vmcnt(40) lgkmcnt(0)
	v_pk_fma_f32 v[196:197], v[162:163], v[126:127], v[196:197]
	v_pk_fma_f32 v[198:199], v[162:163], v[98:99], v[198:199]
	v_pk_fma_f32 v[200:201], v[162:163], v[102:103], v[200:201]
	v_pk_fma_f32 v[202:203], v[162:163], v[106:107], v[202:203]
	v_pk_fma_f32 v[204:205], v[162:163], v[110:111], v[204:205]
	v_pk_fma_f32 v[206:207], v[162:163], v[114:115], v[206:207]
	v_pk_fma_f32 v[208:209], v[162:163], v[118:119], v[208:209]
	v_pk_fma_f32 v[210:211], v[162:163], v[122:123], v[210:211]
	v_pk_fma_f32 v[212:213], v[162:163], v[134:135], v[212:213]
	v_pk_fma_f32 v[196:197], v[164:165], v[128:129], v[196:197]
	v_pk_fma_f32 v[198:199], v[164:165], v[100:101], v[198:199]
	v_pk_fma_f32 v[200:201], v[164:165], v[104:105], v[200:201]
	v_pk_fma_f32 v[202:203], v[164:165], v[108:109], v[202:203]
	v_pk_fma_f32 v[204:205], v[164:165], v[112:113], v[204:205]
	v_pk_fma_f32 v[206:207], v[164:165], v[116:117], v[206:207]
	v_pk_fma_f32 v[208:209], v[164:165], v[120:121], v[208:209]
	v_pk_fma_f32 v[210:211], v[164:165], v[124:125], v[210:211]
	v_pk_fma_f32 v[212:213], v[164:165], v[136:137], v[212:213]
	global_load_dword v162, v[194:195], off nt
	v_add_co_u32_e32 v194, vcc, 0x6000, v194
	v_addc_co_u32_e32 v195, vcc, 0, v195, vcc
	global_load_dword v163, v[194:195], off nt
	v_add_co_u32_e32 v194, vcc, 0x6000, v194
	v_addc_co_u32_e32 v195, vcc, 0, v195, vcc
	global_load_dword v164, v[194:195], off nt
	v_add_co_u32_e32 v194, vcc, 0x6000, v194
	v_addc_co_u32_e32 v195, vcc, 0, v195, vcc
	global_load_dword v165, v[194:195], off nt
	v_add_co_u32_e32 v194, vcc, 0x6000, v194
	v_addc_co_u32_e32 v195, vcc, 0, v195, vcc
	ds_read_b128 v[98:101], v8 offset:4096
	ds_read_b128 v[102:105], v8 offset:8192
	ds_read_b128 v[106:109], v8 offset:12288
	ds_read_b128 v[110:113], v8 offset:16384
	ds_read_b128 v[114:117], v8 offset:20480
	ds_read_b128 v[118:121], v8 offset:24576
	ds_read_b128 v[122:125], v8 offset:28672
	ds_read_b128 v[126:129], v8
	ds_read_b128 v[134:137], v8 offset:32768
	v_add_u32_e32 v8, 16, v8
	s_waitcnt vmcnt(40) lgkmcnt(0)
	v_pk_fma_f32 v[196:197], v[166:167], v[126:127], v[196:197]
	v_pk_fma_f32 v[198:199], v[166:167], v[98:99], v[198:199]
	v_pk_fma_f32 v[200:201], v[166:167], v[102:103], v[200:201]
	v_pk_fma_f32 v[202:203], v[166:167], v[106:107], v[202:203]
	v_pk_fma_f32 v[204:205], v[166:167], v[110:111], v[204:205]
	v_pk_fma_f32 v[206:207], v[166:167], v[114:115], v[206:207]
	v_pk_fma_f32 v[208:209], v[166:167], v[118:119], v[208:209]
	v_pk_fma_f32 v[210:211], v[166:167], v[122:123], v[210:211]
	v_pk_fma_f32 v[212:213], v[166:167], v[134:135], v[212:213]
	v_pk_fma_f32 v[196:197], v[168:169], v[128:129], v[196:197]
	v_pk_fma_f32 v[198:199], v[168:169], v[100:101], v[198:199]
	v_pk_fma_f32 v[200:201], v[168:169], v[104:105], v[200:201]
	v_pk_fma_f32 v[202:203], v[168:169], v[108:109], v[202:203]
	v_pk_fma_f32 v[204:205], v[168:169], v[112:113], v[204:205]
	v_pk_fma_f32 v[206:207], v[168:169], v[116:117], v[206:207]
	v_pk_fma_f32 v[208:209], v[168:169], v[120:121], v[208:209]
	v_pk_fma_f32 v[210:211], v[168:169], v[124:125], v[210:211]
	v_pk_fma_f32 v[212:213], v[168:169], v[136:137], v[212:213]
	global_load_dword v166, v[194:195], off nt
	v_add_co_u32_e32 v194, vcc, 0x6000, v194
	v_addc_co_u32_e32 v195, vcc, 0, v195, vcc
	global_load_dword v167, v[194:195], off nt
	v_add_co_u32_e32 v194, vcc, 0x6000, v194
	v_addc_co_u32_e32 v195, vcc, 0, v195, vcc
	global_load_dword v168, v[194:195], off nt
	v_add_co_u32_e32 v194, vcc, 0x6000, v194
	v_addc_co_u32_e32 v195, vcc, 0, v195, vcc
	global_load_dword v169, v[194:195], off nt
	v_add_co_u32_e32 v194, vcc, 0x6000, v194
	v_addc_co_u32_e32 v195, vcc, 0, v195, vcc
	ds_read_b128 v[98:101], v8 offset:4096
	ds_read_b128 v[102:105], v8 offset:8192
	ds_read_b128 v[106:109], v8 offset:12288
	ds_read_b128 v[110:113], v8 offset:16384
	ds_read_b128 v[114:117], v8 offset:20480
	ds_read_b128 v[118:121], v8 offset:24576
	ds_read_b128 v[122:125], v8 offset:28672
	ds_read_b128 v[126:129], v8
	ds_read_b128 v[134:137], v8 offset:32768
	v_add_u32_e32 v8, 16, v8
	s_waitcnt vmcnt(40) lgkmcnt(0)
	v_pk_fma_f32 v[196:197], v[170:171], v[126:127], v[196:197]
	v_pk_fma_f32 v[198:199], v[170:171], v[98:99], v[198:199]
	v_pk_fma_f32 v[200:201], v[170:171], v[102:103], v[200:201]
	v_pk_fma_f32 v[202:203], v[170:171], v[106:107], v[202:203]
	v_pk_fma_f32 v[204:205], v[170:171], v[110:111], v[204:205]
	v_pk_fma_f32 v[206:207], v[170:171], v[114:115], v[206:207]
	v_pk_fma_f32 v[208:209], v[170:171], v[118:119], v[208:209]
	v_pk_fma_f32 v[210:211], v[170:171], v[122:123], v[210:211]
	v_pk_fma_f32 v[212:213], v[170:171], v[134:135], v[212:213]
	v_pk_fma_f32 v[196:197], v[172:173], v[128:129], v[196:197]
	v_pk_fma_f32 v[198:199], v[172:173], v[100:101], v[198:199]
	v_pk_fma_f32 v[200:201], v[172:173], v[104:105], v[200:201]
	v_pk_fma_f32 v[202:203], v[172:173], v[108:109], v[202:203]
	v_pk_fma_f32 v[204:205], v[172:173], v[112:113], v[204:205]
	v_pk_fma_f32 v[206:207], v[172:173], v[116:117], v[206:207]
	v_pk_fma_f32 v[208:209], v[172:173], v[120:121], v[208:209]
	v_pk_fma_f32 v[210:211], v[172:173], v[124:125], v[210:211]
	v_pk_fma_f32 v[212:213], v[172:173], v[136:137], v[212:213]
	global_load_dword v170, v[194:195], off nt
	v_add_co_u32_e32 v194, vcc, 0x6000, v194
	v_addc_co_u32_e32 v195, vcc, 0, v195, vcc
	global_load_dword v171, v[194:195], off nt
	v_add_co_u32_e32 v194, vcc, 0x6000, v194
	v_addc_co_u32_e32 v195, vcc, 0, v195, vcc
	global_load_dword v172, v[194:195], off nt
	v_add_co_u32_e32 v194, vcc, 0x6000, v194
	v_addc_co_u32_e32 v195, vcc, 0, v195, vcc
	global_load_dword v173, v[194:195], off nt
	v_add_co_u32_e32 v194, vcc, 0x6000, v194
	v_addc_co_u32_e32 v195, vcc, 0, v195, vcc
	ds_read_b128 v[98:101], v8 offset:4096
	ds_read_b128 v[102:105], v8 offset:8192
	ds_read_b128 v[106:109], v8 offset:12288
	ds_read_b128 v[110:113], v8 offset:16384
	ds_read_b128 v[114:117], v8 offset:20480
	ds_read_b128 v[118:121], v8 offset:24576
	ds_read_b128 v[122:125], v8 offset:28672
	ds_read_b128 v[126:129], v8
	ds_read_b128 v[134:137], v8 offset:32768
	v_add_u32_e32 v8, 16, v8
	s_waitcnt vmcnt(40) lgkmcnt(0)
	v_pk_fma_f32 v[196:197], v[174:175], v[126:127], v[196:197]
	v_pk_fma_f32 v[198:199], v[174:175], v[98:99], v[198:199]
	v_pk_fma_f32 v[200:201], v[174:175], v[102:103], v[200:201]
	v_pk_fma_f32 v[202:203], v[174:175], v[106:107], v[202:203]
	v_pk_fma_f32 v[204:205], v[174:175], v[110:111], v[204:205]
	v_pk_fma_f32 v[206:207], v[174:175], v[114:115], v[206:207]
	v_pk_fma_f32 v[208:209], v[174:175], v[118:119], v[208:209]
	v_pk_fma_f32 v[210:211], v[174:175], v[122:123], v[210:211]
	v_pk_fma_f32 v[212:213], v[174:175], v[134:135], v[212:213]
	v_pk_fma_f32 v[196:197], v[176:177], v[128:129], v[196:197]
	v_pk_fma_f32 v[198:199], v[176:177], v[100:101], v[198:199]
	v_pk_fma_f32 v[200:201], v[176:177], v[104:105], v[200:201]
	v_pk_fma_f32 v[202:203], v[176:177], v[108:109], v[202:203]
	v_pk_fma_f32 v[204:205], v[176:177], v[112:113], v[204:205]
	v_pk_fma_f32 v[206:207], v[176:177], v[116:117], v[206:207]
	v_pk_fma_f32 v[208:209], v[176:177], v[120:121], v[208:209]
	v_pk_fma_f32 v[210:211], v[176:177], v[124:125], v[210:211]
	v_pk_fma_f32 v[212:213], v[176:177], v[136:137], v[212:213]
	global_load_dword v174, v[194:195], off nt
	v_add_co_u32_e32 v194, vcc, 0x6000, v194
	v_addc_co_u32_e32 v195, vcc, 0, v195, vcc
	global_load_dword v175, v[194:195], off nt
	v_add_co_u32_e32 v194, vcc, 0x6000, v194
	v_addc_co_u32_e32 v195, vcc, 0, v195, vcc
	global_load_dword v176, v[194:195], off nt
	v_add_co_u32_e32 v194, vcc, 0x6000, v194
	v_addc_co_u32_e32 v195, vcc, 0, v195, vcc
	global_load_dword v177, v[194:195], off nt
	v_add_co_u32_e32 v194, vcc, 0x6000, v194
	v_addc_co_u32_e32 v195, vcc, 0, v195, vcc
	ds_read_b128 v[98:101], v8 offset:4096
	ds_read_b128 v[102:105], v8 offset:8192
	ds_read_b128 v[106:109], v8 offset:12288
	ds_read_b128 v[110:113], v8 offset:16384
	ds_read_b128 v[114:117], v8 offset:20480
	ds_read_b128 v[118:121], v8 offset:24576
	ds_read_b128 v[122:125], v8 offset:28672
	ds_read_b128 v[126:129], v8
	ds_read_b128 v[134:137], v8 offset:32768
	v_add_u32_e32 v8, 16, v8
	s_waitcnt vmcnt(40) lgkmcnt(0)
	v_pk_fma_f32 v[196:197], v[178:179], v[126:127], v[196:197]
	v_pk_fma_f32 v[198:199], v[178:179], v[98:99], v[198:199]
	v_pk_fma_f32 v[200:201], v[178:179], v[102:103], v[200:201]
	v_pk_fma_f32 v[202:203], v[178:179], v[106:107], v[202:203]
	v_pk_fma_f32 v[204:205], v[178:179], v[110:111], v[204:205]
	v_pk_fma_f32 v[206:207], v[178:179], v[114:115], v[206:207]
	v_pk_fma_f32 v[208:209], v[178:179], v[118:119], v[208:209]
	v_pk_fma_f32 v[210:211], v[178:179], v[122:123], v[210:211]
	v_pk_fma_f32 v[212:213], v[178:179], v[134:135], v[212:213]
	v_pk_fma_f32 v[196:197], v[180:181], v[128:129], v[196:197]
	v_pk_fma_f32 v[198:199], v[180:181], v[100:101], v[198:199]
	v_pk_fma_f32 v[200:201], v[180:181], v[104:105], v[200:201]
	v_pk_fma_f32 v[202:203], v[180:181], v[108:109], v[202:203]
	v_pk_fma_f32 v[204:205], v[180:181], v[112:113], v[204:205]
	v_pk_fma_f32 v[206:207], v[180:181], v[116:117], v[206:207]
	v_pk_fma_f32 v[208:209], v[180:181], v[120:121], v[208:209]
	v_pk_fma_f32 v[210:211], v[180:181], v[124:125], v[210:211]
	v_pk_fma_f32 v[212:213], v[180:181], v[136:137], v[212:213]
	global_load_dword v178, v[194:195], off nt
	v_add_co_u32_e32 v194, vcc, 0x6000, v194
	v_addc_co_u32_e32 v195, vcc, 0, v195, vcc
	global_load_dword v179, v[194:195], off nt
	v_add_co_u32_e32 v194, vcc, 0x6000, v194
	v_addc_co_u32_e32 v195, vcc, 0, v195, vcc
	global_load_dword v180, v[194:195], off nt
	v_add_co_u32_e32 v194, vcc, 0x6000, v194
	v_addc_co_u32_e32 v195, vcc, 0, v195, vcc
	global_load_dword v181, v[194:195], off nt
	v_add_co_u32_e32 v194, vcc, 0x6000, v194
	v_addc_co_u32_e32 v195, vcc, 0, v195, vcc
	ds_read_b128 v[98:101], v8 offset:4096
	ds_read_b128 v[102:105], v8 offset:8192
	ds_read_b128 v[106:109], v8 offset:12288
	ds_read_b128 v[110:113], v8 offset:16384
	ds_read_b128 v[114:117], v8 offset:20480
	ds_read_b128 v[118:121], v8 offset:24576
	ds_read_b128 v[122:125], v8 offset:28672
	ds_read_b128 v[126:129], v8
	ds_read_b128 v[134:137], v8 offset:32768
	v_add_u32_e32 v8, 16, v8
	s_waitcnt vmcnt(40) lgkmcnt(0)
	v_pk_fma_f32 v[196:197], v[182:183], v[126:127], v[196:197]
	v_pk_fma_f32 v[198:199], v[182:183], v[98:99], v[198:199]
	v_pk_fma_f32 v[200:201], v[182:183], v[102:103], v[200:201]
	v_pk_fma_f32 v[202:203], v[182:183], v[106:107], v[202:203]
	v_pk_fma_f32 v[204:205], v[182:183], v[110:111], v[204:205]
	v_pk_fma_f32 v[206:207], v[182:183], v[114:115], v[206:207]
	v_pk_fma_f32 v[208:209], v[182:183], v[118:119], v[208:209]
	v_pk_fma_f32 v[210:211], v[182:183], v[122:123], v[210:211]
	v_pk_fma_f32 v[212:213], v[182:183], v[134:135], v[212:213]
	v_pk_fma_f32 v[196:197], v[184:185], v[128:129], v[196:197]
	v_pk_fma_f32 v[198:199], v[184:185], v[100:101], v[198:199]
	v_pk_fma_f32 v[200:201], v[184:185], v[104:105], v[200:201]
	v_pk_fma_f32 v[202:203], v[184:185], v[108:109], v[202:203]
	v_pk_fma_f32 v[204:205], v[184:185], v[112:113], v[204:205]
	v_pk_fma_f32 v[206:207], v[184:185], v[116:117], v[206:207]
	v_pk_fma_f32 v[208:209], v[184:185], v[120:121], v[208:209]
	v_pk_fma_f32 v[210:211], v[184:185], v[124:125], v[210:211]
	v_pk_fma_f32 v[212:213], v[184:185], v[136:137], v[212:213]
	global_load_dword v182, v[194:195], off nt
	v_add_co_u32_e32 v194, vcc, 0x6000, v194
	v_addc_co_u32_e32 v195, vcc, 0, v195, vcc
	global_load_dword v183, v[194:195], off nt
	v_add_co_u32_e32 v194, vcc, 0x6000, v194
	v_addc_co_u32_e32 v195, vcc, 0, v195, vcc
	global_load_dword v184, v[194:195], off nt
	v_add_co_u32_e32 v194, vcc, 0x6000, v194
	v_addc_co_u32_e32 v195, vcc, 0, v195, vcc
	global_load_dword v185, v[194:195], off nt
	v_add_co_u32_e32 v194, vcc, 0x6000, v194
	v_addc_co_u32_e32 v195, vcc, 0, v195, vcc
	ds_read_b128 v[98:101], v8 offset:4096
	ds_read_b128 v[102:105], v8 offset:8192
	ds_read_b128 v[106:109], v8 offset:12288
	ds_read_b128 v[110:113], v8 offset:16384
	ds_read_b128 v[114:117], v8 offset:20480
	ds_read_b128 v[118:121], v8 offset:24576
	ds_read_b128 v[122:125], v8 offset:28672
	ds_read_b128 v[126:129], v8
	ds_read_b128 v[134:137], v8 offset:32768
	v_add_u32_e32 v8, 16, v8
	s_waitcnt vmcnt(40) lgkmcnt(0)
	v_pk_fma_f32 v[196:197], v[186:187], v[126:127], v[196:197]
	v_pk_fma_f32 v[198:199], v[186:187], v[98:99], v[198:199]
	v_pk_fma_f32 v[200:201], v[186:187], v[102:103], v[200:201]
	v_pk_fma_f32 v[202:203], v[186:187], v[106:107], v[202:203]
	v_pk_fma_f32 v[204:205], v[186:187], v[110:111], v[204:205]
	v_pk_fma_f32 v[206:207], v[186:187], v[114:115], v[206:207]
	v_pk_fma_f32 v[208:209], v[186:187], v[118:119], v[208:209]
	v_pk_fma_f32 v[210:211], v[186:187], v[122:123], v[210:211]
	v_pk_fma_f32 v[212:213], v[186:187], v[134:135], v[212:213]
	v_pk_fma_f32 v[196:197], v[188:189], v[128:129], v[196:197]
	v_pk_fma_f32 v[198:199], v[188:189], v[100:101], v[198:199]
	v_pk_fma_f32 v[200:201], v[188:189], v[104:105], v[200:201]
	v_pk_fma_f32 v[202:203], v[188:189], v[108:109], v[202:203]
	v_pk_fma_f32 v[204:205], v[188:189], v[112:113], v[204:205]
	v_pk_fma_f32 v[206:207], v[188:189], v[116:117], v[206:207]
	v_pk_fma_f32 v[208:209], v[188:189], v[120:121], v[208:209]
	v_pk_fma_f32 v[210:211], v[188:189], v[124:125], v[210:211]
	v_pk_fma_f32 v[212:213], v[188:189], v[136:137], v[212:213]
	global_load_dword v186, v[194:195], off nt
	v_add_co_u32_e32 v194, vcc, 0x6000, v194
	v_addc_co_u32_e32 v195, vcc, 0, v195, vcc
	global_load_dword v187, v[194:195], off nt
	v_add_co_u32_e32 v194, vcc, 0x6000, v194
	v_addc_co_u32_e32 v195, vcc, 0, v195, vcc
	global_load_dword v188, v[194:195], off nt
	v_add_co_u32_e32 v194, vcc, 0x6000, v194
	v_addc_co_u32_e32 v195, vcc, 0, v195, vcc
	global_load_dword v189, v[194:195], off nt
	v_add_co_u32_e32 v194, vcc, 0x6000, v194
	v_addc_co_u32_e32 v195, vcc, 0, v195, vcc
	ds_read_b128 v[98:101], v8 offset:4096
	ds_read_b128 v[102:105], v8 offset:8192
	ds_read_b128 v[106:109], v8 offset:12288
	ds_read_b128 v[110:113], v8 offset:16384
	ds_read_b128 v[114:117], v8 offset:20480
	ds_read_b128 v[118:121], v8 offset:24576
	ds_read_b128 v[122:125], v8 offset:28672
	ds_read_b128 v[126:129], v8
	ds_read_b128 v[134:137], v8 offset:32768
	v_add_u32_e32 v8, 16, v8
	s_waitcnt vmcnt(40) lgkmcnt(0)
	v_pk_fma_f32 v[196:197], v[190:191], v[126:127], v[196:197]
	v_pk_fma_f32 v[198:199], v[190:191], v[98:99], v[198:199]
	v_pk_fma_f32 v[200:201], v[190:191], v[102:103], v[200:201]
	v_pk_fma_f32 v[202:203], v[190:191], v[106:107], v[202:203]
	v_pk_fma_f32 v[204:205], v[190:191], v[110:111], v[204:205]
	v_pk_fma_f32 v[206:207], v[190:191], v[114:115], v[206:207]
	v_pk_fma_f32 v[208:209], v[190:191], v[118:119], v[208:209]
	v_pk_fma_f32 v[210:211], v[190:191], v[122:123], v[210:211]
	v_pk_fma_f32 v[212:213], v[190:191], v[134:135], v[212:213]
	v_pk_fma_f32 v[196:197], v[192:193], v[128:129], v[196:197]
	v_pk_fma_f32 v[198:199], v[192:193], v[100:101], v[198:199]
	v_pk_fma_f32 v[200:201], v[192:193], v[104:105], v[200:201]
	v_pk_fma_f32 v[202:203], v[192:193], v[108:109], v[202:203]
	v_pk_fma_f32 v[204:205], v[192:193], v[112:113], v[204:205]
	v_pk_fma_f32 v[206:207], v[192:193], v[116:117], v[206:207]
	v_pk_fma_f32 v[208:209], v[192:193], v[120:121], v[208:209]
	v_pk_fma_f32 v[210:211], v[192:193], v[124:125], v[210:211]
	v_pk_fma_f32 v[212:213], v[192:193], v[136:137], v[212:213]
	global_load_dword v190, v[194:195], off nt
	v_add_co_u32_e32 v194, vcc, 0x6000, v194
	v_addc_co_u32_e32 v195, vcc, 0, v195, vcc
	global_load_dword v191, v[194:195], off nt
	v_add_co_u32_e32 v194, vcc, 0x6000, v194
	v_addc_co_u32_e32 v195, vcc, 0, v195, vcc
	global_load_dword v192, v[194:195], off nt
	v_add_co_u32_e32 v194, vcc, 0x6000, v194
	v_addc_co_u32_e32 v195, vcc, 0, v195, vcc
	global_load_dword v193, v[194:195], off nt
	v_add_co_u32_e32 v194, vcc, 0x6000, v194
	v_addc_co_u32_e32 v195, vcc, 0, v195, vcc
	ds_read_b128 v[98:101], v8 offset:4096
	ds_read_b128 v[102:105], v8 offset:8192
	ds_read_b128 v[106:109], v8 offset:12288
	ds_read_b128 v[110:113], v8 offset:16384
	ds_read_b128 v[114:117], v8 offset:20480
	ds_read_b128 v[118:121], v8 offset:24576
	ds_read_b128 v[122:125], v8 offset:28672
	ds_read_b128 v[126:129], v8
	ds_read_b128 v[134:137], v8 offset:32768
	v_add_u32_e32 v8, 16, v8
	s_waitcnt vmcnt(40) lgkmcnt(0)
	v_pk_fma_f32 v[196:197], v[150:151], v[126:127], v[196:197]
	v_pk_fma_f32 v[198:199], v[150:151], v[98:99], v[198:199]
	v_pk_fma_f32 v[200:201], v[150:151], v[102:103], v[200:201]
	v_pk_fma_f32 v[202:203], v[150:151], v[106:107], v[202:203]
	v_pk_fma_f32 v[204:205], v[150:151], v[110:111], v[204:205]
	v_pk_fma_f32 v[206:207], v[150:151], v[114:115], v[206:207]
	v_pk_fma_f32 v[208:209], v[150:151], v[118:119], v[208:209]
	v_pk_fma_f32 v[210:211], v[150:151], v[122:123], v[210:211]
	v_pk_fma_f32 v[212:213], v[150:151], v[134:135], v[212:213]
	v_pk_fma_f32 v[196:197], v[152:153], v[128:129], v[196:197]
	v_pk_fma_f32 v[198:199], v[152:153], v[100:101], v[198:199]
	v_pk_fma_f32 v[200:201], v[152:153], v[104:105], v[200:201]
	v_pk_fma_f32 v[202:203], v[152:153], v[108:109], v[202:203]
	v_pk_fma_f32 v[204:205], v[152:153], v[112:113], v[204:205]
	v_pk_fma_f32 v[206:207], v[152:153], v[116:117], v[206:207]
	v_pk_fma_f32 v[208:209], v[152:153], v[120:121], v[208:209]
	v_pk_fma_f32 v[210:211], v[152:153], v[124:125], v[210:211]
	v_pk_fma_f32 v[212:213], v[152:153], v[136:137], v[212:213]
	global_load_dword v150, v[194:195], off nt
	v_add_co_u32_e32 v194, vcc, 0x6000, v194
	v_addc_co_u32_e32 v195, vcc, 0, v195, vcc
	global_load_dword v151, v[194:195], off nt
	v_add_co_u32_e32 v194, vcc, 0x6000, v194
	v_addc_co_u32_e32 v195, vcc, 0, v195, vcc
	global_load_dword v152, v[194:195], off nt
	v_add_co_u32_e32 v194, vcc, 0x6000, v194
	v_addc_co_u32_e32 v195, vcc, 0, v195, vcc
	global_load_dword v153, v[194:195], off nt
	v_add_co_u32_e32 v194, vcc, 0x6000, v194
	v_addc_co_u32_e32 v195, vcc, 0, v195, vcc
	ds_read_b128 v[98:101], v8 offset:4096
	ds_read_b128 v[102:105], v8 offset:8192
	ds_read_b128 v[106:109], v8 offset:12288
	ds_read_b128 v[110:113], v8 offset:16384
	ds_read_b128 v[114:117], v8 offset:20480
	ds_read_b128 v[118:121], v8 offset:24576
	ds_read_b128 v[122:125], v8 offset:28672
	ds_read_b128 v[126:129], v8
	ds_read_b128 v[134:137], v8 offset:32768
	v_add_u32_e32 v8, 16, v8
	s_waitcnt vmcnt(40) lgkmcnt(0)
	v_pk_fma_f32 v[196:197], v[154:155], v[126:127], v[196:197]
	v_pk_fma_f32 v[198:199], v[154:155], v[98:99], v[198:199]
	v_pk_fma_f32 v[200:201], v[154:155], v[102:103], v[200:201]
	v_pk_fma_f32 v[202:203], v[154:155], v[106:107], v[202:203]
	v_pk_fma_f32 v[204:205], v[154:155], v[110:111], v[204:205]
	v_pk_fma_f32 v[206:207], v[154:155], v[114:115], v[206:207]
	v_pk_fma_f32 v[208:209], v[154:155], v[118:119], v[208:209]
	v_pk_fma_f32 v[210:211], v[154:155], v[122:123], v[210:211]
	v_pk_fma_f32 v[212:213], v[154:155], v[134:135], v[212:213]
	v_pk_fma_f32 v[196:197], v[156:157], v[128:129], v[196:197]
	v_pk_fma_f32 v[198:199], v[156:157], v[100:101], v[198:199]
	v_pk_fma_f32 v[200:201], v[156:157], v[104:105], v[200:201]
	v_pk_fma_f32 v[202:203], v[156:157], v[108:109], v[202:203]
	v_pk_fma_f32 v[204:205], v[156:157], v[112:113], v[204:205]
	v_pk_fma_f32 v[206:207], v[156:157], v[116:117], v[206:207]
	v_pk_fma_f32 v[208:209], v[156:157], v[120:121], v[208:209]
	v_pk_fma_f32 v[210:211], v[156:157], v[124:125], v[210:211]
	v_pk_fma_f32 v[212:213], v[156:157], v[136:137], v[212:213]
	global_load_dword v154, v[194:195], off nt
	v_add_co_u32_e32 v194, vcc, 0x6000, v194
	v_addc_co_u32_e32 v195, vcc, 0, v195, vcc
	global_load_dword v155, v[194:195], off nt
	v_add_co_u32_e32 v194, vcc, 0x6000, v194
	v_addc_co_u32_e32 v195, vcc, 0, v195, vcc
	global_load_dword v156, v[194:195], off nt
	v_add_co_u32_e32 v194, vcc, 0x6000, v194
	v_addc_co_u32_e32 v195, vcc, 0, v195, vcc
	global_load_dword v157, v[194:195], off nt
	v_add_co_u32_e32 v194, vcc, 0x6000, v194
	v_addc_co_u32_e32 v195, vcc, 0, v195, vcc
	ds_read_b128 v[98:101], v8 offset:4096
	ds_read_b128 v[102:105], v8 offset:8192
	ds_read_b128 v[106:109], v8 offset:12288
	ds_read_b128 v[110:113], v8 offset:16384
	ds_read_b128 v[114:117], v8 offset:20480
	ds_read_b128 v[118:121], v8 offset:24576
	ds_read_b128 v[122:125], v8 offset:28672
	ds_read_b128 v[126:129], v8
	ds_read_b128 v[134:137], v8 offset:32768
	v_add_u32_e32 v8, 16, v8
	s_waitcnt vmcnt(40) lgkmcnt(0)
	v_pk_fma_f32 v[196:197], v[158:159], v[126:127], v[196:197]
	v_pk_fma_f32 v[198:199], v[158:159], v[98:99], v[198:199]
	v_pk_fma_f32 v[200:201], v[158:159], v[102:103], v[200:201]
	v_pk_fma_f32 v[202:203], v[158:159], v[106:107], v[202:203]
	v_pk_fma_f32 v[204:205], v[158:159], v[110:111], v[204:205]
	v_pk_fma_f32 v[206:207], v[158:159], v[114:115], v[206:207]
	v_pk_fma_f32 v[208:209], v[158:159], v[118:119], v[208:209]
	v_pk_fma_f32 v[210:211], v[158:159], v[122:123], v[210:211]
	v_pk_fma_f32 v[212:213], v[158:159], v[134:135], v[212:213]
	v_pk_fma_f32 v[196:197], v[160:161], v[128:129], v[196:197]
	v_pk_fma_f32 v[198:199], v[160:161], v[100:101], v[198:199]
	v_pk_fma_f32 v[200:201], v[160:161], v[104:105], v[200:201]
	v_pk_fma_f32 v[202:203], v[160:161], v[108:109], v[202:203]
	v_pk_fma_f32 v[204:205], v[160:161], v[112:113], v[204:205]
	v_pk_fma_f32 v[206:207], v[160:161], v[116:117], v[206:207]
	v_pk_fma_f32 v[208:209], v[160:161], v[120:121], v[208:209]
	v_pk_fma_f32 v[210:211], v[160:161], v[124:125], v[210:211]
	v_pk_fma_f32 v[212:213], v[160:161], v[136:137], v[212:213]
	global_load_dword v158, v[194:195], off nt
	v_add_co_u32_e32 v194, vcc, 0x6000, v194
	v_addc_co_u32_e32 v195, vcc, 0, v195, vcc
	global_load_dword v159, v[194:195], off nt
	v_add_co_u32_e32 v194, vcc, 0x6000, v194
	v_addc_co_u32_e32 v195, vcc, 0, v195, vcc
	global_load_dword v160, v[194:195], off nt
	v_add_co_u32_e32 v194, vcc, 0x6000, v194
	v_addc_co_u32_e32 v195, vcc, 0, v195, vcc
	global_load_dword v161, v[194:195], off nt
	v_add_co_u32_e32 v194, vcc, 0x6000, v194
	v_addc_co_u32_e32 v195, vcc, 0, v195, vcc
	ds_read_b128 v[98:101], v8 offset:4096
	ds_read_b128 v[102:105], v8 offset:8192
	ds_read_b128 v[106:109], v8 offset:12288
	ds_read_b128 v[110:113], v8 offset:16384
	ds_read_b128 v[114:117], v8 offset:20480
	ds_read_b128 v[118:121], v8 offset:24576
	ds_read_b128 v[122:125], v8 offset:28672
	ds_read_b128 v[126:129], v8
	ds_read_b128 v[134:137], v8 offset:32768
	v_add_u32_e32 v8, 16, v8
	s_waitcnt vmcnt(40) lgkmcnt(0)
	v_pk_fma_f32 v[196:197], v[162:163], v[126:127], v[196:197]
	v_pk_fma_f32 v[198:199], v[162:163], v[98:99], v[198:199]
	v_pk_fma_f32 v[200:201], v[162:163], v[102:103], v[200:201]
	v_pk_fma_f32 v[202:203], v[162:163], v[106:107], v[202:203]
	v_pk_fma_f32 v[204:205], v[162:163], v[110:111], v[204:205]
	v_pk_fma_f32 v[206:207], v[162:163], v[114:115], v[206:207]
	v_pk_fma_f32 v[208:209], v[162:163], v[118:119], v[208:209]
	v_pk_fma_f32 v[210:211], v[162:163], v[122:123], v[210:211]
	v_pk_fma_f32 v[212:213], v[162:163], v[134:135], v[212:213]
	v_pk_fma_f32 v[196:197], v[164:165], v[128:129], v[196:197]
	v_pk_fma_f32 v[198:199], v[164:165], v[100:101], v[198:199]
	v_pk_fma_f32 v[200:201], v[164:165], v[104:105], v[200:201]
	v_pk_fma_f32 v[202:203], v[164:165], v[108:109], v[202:203]
	v_pk_fma_f32 v[204:205], v[164:165], v[112:113], v[204:205]
	v_pk_fma_f32 v[206:207], v[164:165], v[116:117], v[206:207]
	v_pk_fma_f32 v[208:209], v[164:165], v[120:121], v[208:209]
	v_pk_fma_f32 v[210:211], v[164:165], v[124:125], v[210:211]
	v_pk_fma_f32 v[212:213], v[164:165], v[136:137], v[212:213]
	global_load_dword v162, v[194:195], off nt
	v_add_co_u32_e32 v194, vcc, 0x6000, v194
	v_addc_co_u32_e32 v195, vcc, 0, v195, vcc
	global_load_dword v163, v[194:195], off nt
	v_add_co_u32_e32 v194, vcc, 0x6000, v194
	v_addc_co_u32_e32 v195, vcc, 0, v195, vcc
	global_load_dword v164, v[194:195], off nt
	v_add_co_u32_e32 v194, vcc, 0x6000, v194
	v_addc_co_u32_e32 v195, vcc, 0, v195, vcc
	global_load_dword v165, v[194:195], off nt
	v_add_co_u32_e32 v194, vcc, 0x6000, v194
	v_addc_co_u32_e32 v195, vcc, 0, v195, vcc
	ds_read_b128 v[98:101], v8 offset:4096
	ds_read_b128 v[102:105], v8 offset:8192
	ds_read_b128 v[106:109], v8 offset:12288
	ds_read_b128 v[110:113], v8 offset:16384
	ds_read_b128 v[114:117], v8 offset:20480
	ds_read_b128 v[118:121], v8 offset:24576
	ds_read_b128 v[122:125], v8 offset:28672
	ds_read_b128 v[126:129], v8
	ds_read_b128 v[134:137], v8 offset:32768
	v_add_u32_e32 v8, 16, v8
	s_waitcnt vmcnt(40) lgkmcnt(0)
	v_pk_fma_f32 v[196:197], v[166:167], v[126:127], v[196:197]
	v_pk_fma_f32 v[198:199], v[166:167], v[98:99], v[198:199]
	v_pk_fma_f32 v[200:201], v[166:167], v[102:103], v[200:201]
	v_pk_fma_f32 v[202:203], v[166:167], v[106:107], v[202:203]
	v_pk_fma_f32 v[204:205], v[166:167], v[110:111], v[204:205]
	v_pk_fma_f32 v[206:207], v[166:167], v[114:115], v[206:207]
	v_pk_fma_f32 v[208:209], v[166:167], v[118:119], v[208:209]
	v_pk_fma_f32 v[210:211], v[166:167], v[122:123], v[210:211]
	v_pk_fma_f32 v[212:213], v[166:167], v[134:135], v[212:213]
	v_pk_fma_f32 v[196:197], v[168:169], v[128:129], v[196:197]
	v_pk_fma_f32 v[198:199], v[168:169], v[100:101], v[198:199]
	v_pk_fma_f32 v[200:201], v[168:169], v[104:105], v[200:201]
	v_pk_fma_f32 v[202:203], v[168:169], v[108:109], v[202:203]
	v_pk_fma_f32 v[204:205], v[168:169], v[112:113], v[204:205]
	v_pk_fma_f32 v[206:207], v[168:169], v[116:117], v[206:207]
	v_pk_fma_f32 v[208:209], v[168:169], v[120:121], v[208:209]
	v_pk_fma_f32 v[210:211], v[168:169], v[124:125], v[210:211]
	v_pk_fma_f32 v[212:213], v[168:169], v[136:137], v[212:213]
	global_load_dword v166, v[194:195], off nt
	v_add_co_u32_e32 v194, vcc, 0x6000, v194
	v_addc_co_u32_e32 v195, vcc, 0, v195, vcc
	global_load_dword v167, v[194:195], off nt
	v_add_co_u32_e32 v194, vcc, 0x6000, v194
	v_addc_co_u32_e32 v195, vcc, 0, v195, vcc
	global_load_dword v168, v[194:195], off nt
	v_add_co_u32_e32 v194, vcc, 0x6000, v194
	v_addc_co_u32_e32 v195, vcc, 0, v195, vcc
	global_load_dword v169, v[194:195], off nt
	v_add_co_u32_e32 v194, vcc, 0x6000, v194
	v_addc_co_u32_e32 v195, vcc, 0, v195, vcc
	ds_read_b128 v[98:101], v8 offset:4096
	ds_read_b128 v[102:105], v8 offset:8192
	ds_read_b128 v[106:109], v8 offset:12288
	ds_read_b128 v[110:113], v8 offset:16384
	ds_read_b128 v[114:117], v8 offset:20480
	ds_read_b128 v[118:121], v8 offset:24576
	ds_read_b128 v[122:125], v8 offset:28672
	ds_read_b128 v[126:129], v8
	ds_read_b128 v[134:137], v8 offset:32768
	v_add_u32_e32 v8, 16, v8
	s_waitcnt vmcnt(40) lgkmcnt(0)
	v_pk_fma_f32 v[196:197], v[170:171], v[126:127], v[196:197]
	v_pk_fma_f32 v[198:199], v[170:171], v[98:99], v[198:199]
	v_pk_fma_f32 v[200:201], v[170:171], v[102:103], v[200:201]
	v_pk_fma_f32 v[202:203], v[170:171], v[106:107], v[202:203]
	v_pk_fma_f32 v[204:205], v[170:171], v[110:111], v[204:205]
	v_pk_fma_f32 v[206:207], v[170:171], v[114:115], v[206:207]
	v_pk_fma_f32 v[208:209], v[170:171], v[118:119], v[208:209]
	v_pk_fma_f32 v[210:211], v[170:171], v[122:123], v[210:211]
	v_pk_fma_f32 v[212:213], v[170:171], v[134:135], v[212:213]
	v_pk_fma_f32 v[196:197], v[172:173], v[128:129], v[196:197]
	v_pk_fma_f32 v[198:199], v[172:173], v[100:101], v[198:199]
	v_pk_fma_f32 v[200:201], v[172:173], v[104:105], v[200:201]
	v_pk_fma_f32 v[202:203], v[172:173], v[108:109], v[202:203]
	v_pk_fma_f32 v[204:205], v[172:173], v[112:113], v[204:205]
	v_pk_fma_f32 v[206:207], v[172:173], v[116:117], v[206:207]
	v_pk_fma_f32 v[208:209], v[172:173], v[120:121], v[208:209]
	v_pk_fma_f32 v[210:211], v[172:173], v[124:125], v[210:211]
	v_pk_fma_f32 v[212:213], v[172:173], v[136:137], v[212:213]
	global_load_dword v170, v[194:195], off nt
	v_add_co_u32_e32 v194, vcc, 0x6000, v194
	v_addc_co_u32_e32 v195, vcc, 0, v195, vcc
	global_load_dword v171, v[194:195], off nt
	v_add_co_u32_e32 v194, vcc, 0x6000, v194
	v_addc_co_u32_e32 v195, vcc, 0, v195, vcc
	global_load_dword v172, v[194:195], off nt
	v_add_co_u32_e32 v194, vcc, 0x6000, v194
	v_addc_co_u32_e32 v195, vcc, 0, v195, vcc
	global_load_dword v173, v[194:195], off nt
	v_add_co_u32_e32 v194, vcc, 0x6000, v194
	v_addc_co_u32_e32 v195, vcc, 0, v195, vcc
	ds_read_b128 v[98:101], v8 offset:4096
	ds_read_b128 v[102:105], v8 offset:8192
	ds_read_b128 v[106:109], v8 offset:12288
	ds_read_b128 v[110:113], v8 offset:16384
	ds_read_b128 v[114:117], v8 offset:20480
	ds_read_b128 v[118:121], v8 offset:24576
	ds_read_b128 v[122:125], v8 offset:28672
	ds_read_b128 v[126:129], v8
	ds_read_b128 v[134:137], v8 offset:32768
	v_add_u32_e32 v8, 16, v8
	s_waitcnt vmcnt(40) lgkmcnt(0)
	v_pk_fma_f32 v[196:197], v[174:175], v[126:127], v[196:197]
	v_pk_fma_f32 v[198:199], v[174:175], v[98:99], v[198:199]
	v_pk_fma_f32 v[200:201], v[174:175], v[102:103], v[200:201]
	v_pk_fma_f32 v[202:203], v[174:175], v[106:107], v[202:203]
	v_pk_fma_f32 v[204:205], v[174:175], v[110:111], v[204:205]
	v_pk_fma_f32 v[206:207], v[174:175], v[114:115], v[206:207]
	v_pk_fma_f32 v[208:209], v[174:175], v[118:119], v[208:209]
	v_pk_fma_f32 v[210:211], v[174:175], v[122:123], v[210:211]
	v_pk_fma_f32 v[212:213], v[174:175], v[134:135], v[212:213]
	v_pk_fma_f32 v[196:197], v[176:177], v[128:129], v[196:197]
	v_pk_fma_f32 v[198:199], v[176:177], v[100:101], v[198:199]
	v_pk_fma_f32 v[200:201], v[176:177], v[104:105], v[200:201]
	v_pk_fma_f32 v[202:203], v[176:177], v[108:109], v[202:203]
	v_pk_fma_f32 v[204:205], v[176:177], v[112:113], v[204:205]
	v_pk_fma_f32 v[206:207], v[176:177], v[116:117], v[206:207]
	v_pk_fma_f32 v[208:209], v[176:177], v[120:121], v[208:209]
	v_pk_fma_f32 v[210:211], v[176:177], v[124:125], v[210:211]
	v_pk_fma_f32 v[212:213], v[176:177], v[136:137], v[212:213]
	global_load_dword v174, v[194:195], off nt
	v_add_co_u32_e32 v194, vcc, 0x6000, v194
	v_addc_co_u32_e32 v195, vcc, 0, v195, vcc
	global_load_dword v175, v[194:195], off nt
	v_add_co_u32_e32 v194, vcc, 0x6000, v194
	v_addc_co_u32_e32 v195, vcc, 0, v195, vcc
	global_load_dword v176, v[194:195], off nt
	v_add_co_u32_e32 v194, vcc, 0x6000, v194
	v_addc_co_u32_e32 v195, vcc, 0, v195, vcc
	global_load_dword v177, v[194:195], off nt
	v_add_co_u32_e32 v194, vcc, 0x6000, v194
	v_addc_co_u32_e32 v195, vcc, 0, v195, vcc
	ds_read_b128 v[98:101], v8 offset:4096
	ds_read_b128 v[102:105], v8 offset:8192
	ds_read_b128 v[106:109], v8 offset:12288
	ds_read_b128 v[110:113], v8 offset:16384
	ds_read_b128 v[114:117], v8 offset:20480
	ds_read_b128 v[118:121], v8 offset:24576
	ds_read_b128 v[122:125], v8 offset:28672
	ds_read_b128 v[126:129], v8
	ds_read_b128 v[134:137], v8 offset:32768
	v_add_u32_e32 v8, 16, v8
	s_waitcnt vmcnt(40) lgkmcnt(0)
	v_pk_fma_f32 v[196:197], v[178:179], v[126:127], v[196:197]
	v_pk_fma_f32 v[198:199], v[178:179], v[98:99], v[198:199]
	v_pk_fma_f32 v[200:201], v[178:179], v[102:103], v[200:201]
	v_pk_fma_f32 v[202:203], v[178:179], v[106:107], v[202:203]
	v_pk_fma_f32 v[204:205], v[178:179], v[110:111], v[204:205]
	v_pk_fma_f32 v[206:207], v[178:179], v[114:115], v[206:207]
	v_pk_fma_f32 v[208:209], v[178:179], v[118:119], v[208:209]
	v_pk_fma_f32 v[210:211], v[178:179], v[122:123], v[210:211]
	v_pk_fma_f32 v[212:213], v[178:179], v[134:135], v[212:213]
	v_pk_fma_f32 v[196:197], v[180:181], v[128:129], v[196:197]
	v_pk_fma_f32 v[198:199], v[180:181], v[100:101], v[198:199]
	v_pk_fma_f32 v[200:201], v[180:181], v[104:105], v[200:201]
	v_pk_fma_f32 v[202:203], v[180:181], v[108:109], v[202:203]
	v_pk_fma_f32 v[204:205], v[180:181], v[112:113], v[204:205]
	v_pk_fma_f32 v[206:207], v[180:181], v[116:117], v[206:207]
	v_pk_fma_f32 v[208:209], v[180:181], v[120:121], v[208:209]
	v_pk_fma_f32 v[210:211], v[180:181], v[124:125], v[210:211]
	v_pk_fma_f32 v[212:213], v[180:181], v[136:137], v[212:213]
	global_load_dword v178, v[194:195], off nt
	v_add_co_u32_e32 v194, vcc, 0x6000, v194
	v_addc_co_u32_e32 v195, vcc, 0, v195, vcc
	global_load_dword v179, v[194:195], off nt
	v_add_co_u32_e32 v194, vcc, 0x6000, v194
	v_addc_co_u32_e32 v195, vcc, 0, v195, vcc
	global_load_dword v180, v[194:195], off nt
	v_add_co_u32_e32 v194, vcc, 0x6000, v194
	v_addc_co_u32_e32 v195, vcc, 0, v195, vcc
	global_load_dword v181, v[194:195], off nt
	v_add_co_u32_e32 v194, vcc, 0x6000, v194
	v_addc_co_u32_e32 v195, vcc, 0, v195, vcc
	ds_read_b128 v[98:101], v8 offset:4096
	ds_read_b128 v[102:105], v8 offset:8192
	ds_read_b128 v[106:109], v8 offset:12288
	ds_read_b128 v[110:113], v8 offset:16384
	ds_read_b128 v[114:117], v8 offset:20480
	ds_read_b128 v[118:121], v8 offset:24576
	ds_read_b128 v[122:125], v8 offset:28672
	ds_read_b128 v[126:129], v8
	ds_read_b128 v[134:137], v8 offset:32768
	v_add_u32_e32 v8, 16, v8
	s_waitcnt vmcnt(40) lgkmcnt(0)
	v_pk_fma_f32 v[196:197], v[182:183], v[126:127], v[196:197]
	v_pk_fma_f32 v[198:199], v[182:183], v[98:99], v[198:199]
	v_pk_fma_f32 v[200:201], v[182:183], v[102:103], v[200:201]
	v_pk_fma_f32 v[202:203], v[182:183], v[106:107], v[202:203]
	v_pk_fma_f32 v[204:205], v[182:183], v[110:111], v[204:205]
	v_pk_fma_f32 v[206:207], v[182:183], v[114:115], v[206:207]
	v_pk_fma_f32 v[208:209], v[182:183], v[118:119], v[208:209]
	v_pk_fma_f32 v[210:211], v[182:183], v[122:123], v[210:211]
	v_pk_fma_f32 v[212:213], v[182:183], v[134:135], v[212:213]
	v_pk_fma_f32 v[196:197], v[184:185], v[128:129], v[196:197]
	v_pk_fma_f32 v[198:199], v[184:185], v[100:101], v[198:199]
	v_pk_fma_f32 v[200:201], v[184:185], v[104:105], v[200:201]
	v_pk_fma_f32 v[202:203], v[184:185], v[108:109], v[202:203]
	v_pk_fma_f32 v[204:205], v[184:185], v[112:113], v[204:205]
	v_pk_fma_f32 v[206:207], v[184:185], v[116:117], v[206:207]
	v_pk_fma_f32 v[208:209], v[184:185], v[120:121], v[208:209]
	v_pk_fma_f32 v[210:211], v[184:185], v[124:125], v[210:211]
	v_pk_fma_f32 v[212:213], v[184:185], v[136:137], v[212:213]
	global_load_dword v182, v[194:195], off nt
	v_add_co_u32_e32 v194, vcc, 0x6000, v194
	v_addc_co_u32_e32 v195, vcc, 0, v195, vcc
	global_load_dword v183, v[194:195], off nt
	v_add_co_u32_e32 v194, vcc, 0x6000, v194
	v_addc_co_u32_e32 v195, vcc, 0, v195, vcc
	global_load_dword v184, v[194:195], off nt
	v_add_co_u32_e32 v194, vcc, 0x6000, v194
	v_addc_co_u32_e32 v195, vcc, 0, v195, vcc
	global_load_dword v185, v[194:195], off nt
	v_add_co_u32_e32 v194, vcc, 0x6000, v194
	v_addc_co_u32_e32 v195, vcc, 0, v195, vcc
	ds_read_b128 v[98:101], v8 offset:4096
	ds_read_b128 v[102:105], v8 offset:8192
	ds_read_b128 v[106:109], v8 offset:12288
	ds_read_b128 v[110:113], v8 offset:16384
	ds_read_b128 v[114:117], v8 offset:20480
	ds_read_b128 v[118:121], v8 offset:24576
	ds_read_b128 v[122:125], v8 offset:28672
	ds_read_b128 v[126:129], v8
	ds_read_b128 v[134:137], v8 offset:32768
	v_add_u32_e32 v8, 16, v8
	s_waitcnt vmcnt(40) lgkmcnt(0)
	v_pk_fma_f32 v[196:197], v[186:187], v[126:127], v[196:197]
	v_pk_fma_f32 v[198:199], v[186:187], v[98:99], v[198:199]
	v_pk_fma_f32 v[200:201], v[186:187], v[102:103], v[200:201]
	v_pk_fma_f32 v[202:203], v[186:187], v[106:107], v[202:203]
	v_pk_fma_f32 v[204:205], v[186:187], v[110:111], v[204:205]
	v_pk_fma_f32 v[206:207], v[186:187], v[114:115], v[206:207]
	v_pk_fma_f32 v[208:209], v[186:187], v[118:119], v[208:209]
	v_pk_fma_f32 v[210:211], v[186:187], v[122:123], v[210:211]
	v_pk_fma_f32 v[212:213], v[186:187], v[134:135], v[212:213]
	v_pk_fma_f32 v[196:197], v[188:189], v[128:129], v[196:197]
	v_pk_fma_f32 v[198:199], v[188:189], v[100:101], v[198:199]
	v_pk_fma_f32 v[200:201], v[188:189], v[104:105], v[200:201]
	v_pk_fma_f32 v[202:203], v[188:189], v[108:109], v[202:203]
	v_pk_fma_f32 v[204:205], v[188:189], v[112:113], v[204:205]
	v_pk_fma_f32 v[206:207], v[188:189], v[116:117], v[206:207]
	v_pk_fma_f32 v[208:209], v[188:189], v[120:121], v[208:209]
	v_pk_fma_f32 v[210:211], v[188:189], v[124:125], v[210:211]
	v_pk_fma_f32 v[212:213], v[188:189], v[136:137], v[212:213]
	global_load_dword v186, v[194:195], off nt
	v_add_co_u32_e32 v194, vcc, 0x6000, v194
	v_addc_co_u32_e32 v195, vcc, 0, v195, vcc
	global_load_dword v187, v[194:195], off nt
	v_add_co_u32_e32 v194, vcc, 0x6000, v194
	v_addc_co_u32_e32 v195, vcc, 0, v195, vcc
	global_load_dword v188, v[194:195], off nt
	v_add_co_u32_e32 v194, vcc, 0x6000, v194
	v_addc_co_u32_e32 v195, vcc, 0, v195, vcc
	global_load_dword v189, v[194:195], off nt
	ds_read_b128 v[98:101], v8 offset:4096
	ds_read_b128 v[102:105], v8 offset:8192
	ds_read_b128 v[106:109], v8 offset:12288
	ds_read_b128 v[110:113], v8 offset:16384
	ds_read_b128 v[114:117], v8 offset:20480
	ds_read_b128 v[118:121], v8 offset:24576
	ds_read_b128 v[122:125], v8 offset:28672
	ds_read_b128 v[126:129], v8
	ds_read_b128 v[134:137], v8 offset:32768
	v_add_u32_e32 v8, 16, v8
	s_waitcnt vmcnt(40) lgkmcnt(0)
	v_pk_fma_f32 v[196:197], v[190:191], v[126:127], v[196:197]
	v_pk_fma_f32 v[198:199], v[190:191], v[98:99], v[198:199]
	v_pk_fma_f32 v[200:201], v[190:191], v[102:103], v[200:201]
	v_pk_fma_f32 v[202:203], v[190:191], v[106:107], v[202:203]
	v_pk_fma_f32 v[204:205], v[190:191], v[110:111], v[204:205]
	v_pk_fma_f32 v[206:207], v[190:191], v[114:115], v[206:207]
	v_pk_fma_f32 v[208:209], v[190:191], v[118:119], v[208:209]
	v_pk_fma_f32 v[210:211], v[190:191], v[122:123], v[210:211]
	v_pk_fma_f32 v[212:213], v[190:191], v[134:135], v[212:213]
	v_pk_fma_f32 v[196:197], v[192:193], v[128:129], v[196:197]
	v_pk_fma_f32 v[198:199], v[192:193], v[100:101], v[198:199]
	v_pk_fma_f32 v[200:201], v[192:193], v[104:105], v[200:201]
	v_pk_fma_f32 v[202:203], v[192:193], v[108:109], v[202:203]
	v_pk_fma_f32 v[204:205], v[192:193], v[112:113], v[204:205]
	v_pk_fma_f32 v[206:207], v[192:193], v[116:117], v[206:207]
	v_pk_fma_f32 v[208:209], v[192:193], v[120:121], v[208:209]
	v_pk_fma_f32 v[210:211], v[192:193], v[124:125], v[210:211]
	v_pk_fma_f32 v[212:213], v[192:193], v[136:137], v[212:213]
	ds_read_b128 v[98:101], v8 offset:4096
	ds_read_b128 v[102:105], v8 offset:8192
	ds_read_b128 v[106:109], v8 offset:12288
	ds_read_b128 v[110:113], v8 offset:16384
	ds_read_b128 v[114:117], v8 offset:20480
	ds_read_b128 v[118:121], v8 offset:24576
	ds_read_b128 v[122:125], v8 offset:28672
	ds_read_b128 v[126:129], v8
	ds_read_b128 v[134:137], v8 offset:32768
	v_add_u32_e32 v8, 16, v8
	s_waitcnt vmcnt(36) lgkmcnt(0)
	v_pk_fma_f32 v[196:197], v[150:151], v[126:127], v[196:197]
	v_pk_fma_f32 v[198:199], v[150:151], v[98:99], v[198:199]
	v_pk_fma_f32 v[200:201], v[150:151], v[102:103], v[200:201]
	v_pk_fma_f32 v[202:203], v[150:151], v[106:107], v[202:203]
	v_pk_fma_f32 v[204:205], v[150:151], v[110:111], v[204:205]
	v_pk_fma_f32 v[206:207], v[150:151], v[114:115], v[206:207]
	v_pk_fma_f32 v[208:209], v[150:151], v[118:119], v[208:209]
	v_pk_fma_f32 v[210:211], v[150:151], v[122:123], v[210:211]
	v_pk_fma_f32 v[212:213], v[150:151], v[134:135], v[212:213]
	v_pk_fma_f32 v[196:197], v[152:153], v[128:129], v[196:197]
	v_pk_fma_f32 v[198:199], v[152:153], v[100:101], v[198:199]
	v_pk_fma_f32 v[200:201], v[152:153], v[104:105], v[200:201]
	v_pk_fma_f32 v[202:203], v[152:153], v[108:109], v[202:203]
	v_pk_fma_f32 v[204:205], v[152:153], v[112:113], v[204:205]
	v_pk_fma_f32 v[206:207], v[152:153], v[116:117], v[206:207]
	v_pk_fma_f32 v[208:209], v[152:153], v[120:121], v[208:209]
	v_pk_fma_f32 v[210:211], v[152:153], v[124:125], v[210:211]
	v_pk_fma_f32 v[212:213], v[152:153], v[136:137], v[212:213]
	ds_read_b128 v[98:101], v8 offset:4096
	ds_read_b128 v[102:105], v8 offset:8192
	ds_read_b128 v[106:109], v8 offset:12288
	ds_read_b128 v[110:113], v8 offset:16384
	ds_read_b128 v[114:117], v8 offset:20480
	ds_read_b128 v[118:121], v8 offset:24576
	ds_read_b128 v[122:125], v8 offset:28672
	ds_read_b128 v[126:129], v8
	ds_read_b128 v[134:137], v8 offset:32768
	v_add_u32_e32 v8, 16, v8
	s_waitcnt vmcnt(32) lgkmcnt(0)
	v_pk_fma_f32 v[196:197], v[154:155], v[126:127], v[196:197]
	v_pk_fma_f32 v[198:199], v[154:155], v[98:99], v[198:199]
	v_pk_fma_f32 v[200:201], v[154:155], v[102:103], v[200:201]
	v_pk_fma_f32 v[202:203], v[154:155], v[106:107], v[202:203]
	v_pk_fma_f32 v[204:205], v[154:155], v[110:111], v[204:205]
	v_pk_fma_f32 v[206:207], v[154:155], v[114:115], v[206:207]
	v_pk_fma_f32 v[208:209], v[154:155], v[118:119], v[208:209]
	v_pk_fma_f32 v[210:211], v[154:155], v[122:123], v[210:211]
	v_pk_fma_f32 v[212:213], v[154:155], v[134:135], v[212:213]
	v_pk_fma_f32 v[196:197], v[156:157], v[128:129], v[196:197]
	v_pk_fma_f32 v[198:199], v[156:157], v[100:101], v[198:199]
	v_pk_fma_f32 v[200:201], v[156:157], v[104:105], v[200:201]
	v_pk_fma_f32 v[202:203], v[156:157], v[108:109], v[202:203]
	v_pk_fma_f32 v[204:205], v[156:157], v[112:113], v[204:205]
	v_pk_fma_f32 v[206:207], v[156:157], v[116:117], v[206:207]
	v_pk_fma_f32 v[208:209], v[156:157], v[120:121], v[208:209]
	v_pk_fma_f32 v[210:211], v[156:157], v[124:125], v[210:211]
	v_pk_fma_f32 v[212:213], v[156:157], v[136:137], v[212:213]
	ds_read_b128 v[98:101], v8 offset:4096
	ds_read_b128 v[102:105], v8 offset:8192
	ds_read_b128 v[106:109], v8 offset:12288
	ds_read_b128 v[110:113], v8 offset:16384
	ds_read_b128 v[114:117], v8 offset:20480
	ds_read_b128 v[118:121], v8 offset:24576
	ds_read_b128 v[122:125], v8 offset:28672
	ds_read_b128 v[126:129], v8
	ds_read_b128 v[134:137], v8 offset:32768
	v_add_u32_e32 v8, 16, v8
	s_waitcnt vmcnt(28) lgkmcnt(0)
	v_pk_fma_f32 v[196:197], v[158:159], v[126:127], v[196:197]
	v_pk_fma_f32 v[198:199], v[158:159], v[98:99], v[198:199]
	v_pk_fma_f32 v[200:201], v[158:159], v[102:103], v[200:201]
	v_pk_fma_f32 v[202:203], v[158:159], v[106:107], v[202:203]
	v_pk_fma_f32 v[204:205], v[158:159], v[110:111], v[204:205]
	v_pk_fma_f32 v[206:207], v[158:159], v[114:115], v[206:207]
	v_pk_fma_f32 v[208:209], v[158:159], v[118:119], v[208:209]
	v_pk_fma_f32 v[210:211], v[158:159], v[122:123], v[210:211]
	v_pk_fma_f32 v[212:213], v[158:159], v[134:135], v[212:213]
	v_pk_fma_f32 v[196:197], v[160:161], v[128:129], v[196:197]
	v_pk_fma_f32 v[198:199], v[160:161], v[100:101], v[198:199]
	v_pk_fma_f32 v[200:201], v[160:161], v[104:105], v[200:201]
	v_pk_fma_f32 v[202:203], v[160:161], v[108:109], v[202:203]
	v_pk_fma_f32 v[204:205], v[160:161], v[112:113], v[204:205]
	v_pk_fma_f32 v[206:207], v[160:161], v[116:117], v[206:207]
	v_pk_fma_f32 v[208:209], v[160:161], v[120:121], v[208:209]
	v_pk_fma_f32 v[210:211], v[160:161], v[124:125], v[210:211]
	v_pk_fma_f32 v[212:213], v[160:161], v[136:137], v[212:213]
	ds_read_b128 v[98:101], v8 offset:4096
	ds_read_b128 v[102:105], v8 offset:8192
	ds_read_b128 v[106:109], v8 offset:12288
	ds_read_b128 v[110:113], v8 offset:16384
	ds_read_b128 v[114:117], v8 offset:20480
	ds_read_b128 v[118:121], v8 offset:24576
	ds_read_b128 v[122:125], v8 offset:28672
	ds_read_b128 v[126:129], v8
	ds_read_b128 v[134:137], v8 offset:32768
	v_add_u32_e32 v8, 16, v8
	s_waitcnt vmcnt(24) lgkmcnt(0)
	v_pk_fma_f32 v[196:197], v[162:163], v[126:127], v[196:197]
	v_pk_fma_f32 v[198:199], v[162:163], v[98:99], v[198:199]
	v_pk_fma_f32 v[200:201], v[162:163], v[102:103], v[200:201]
	v_pk_fma_f32 v[202:203], v[162:163], v[106:107], v[202:203]
	v_pk_fma_f32 v[204:205], v[162:163], v[110:111], v[204:205]
	v_pk_fma_f32 v[206:207], v[162:163], v[114:115], v[206:207]
	v_pk_fma_f32 v[208:209], v[162:163], v[118:119], v[208:209]
	v_pk_fma_f32 v[210:211], v[162:163], v[122:123], v[210:211]
	v_pk_fma_f32 v[212:213], v[162:163], v[134:135], v[212:213]
	v_pk_fma_f32 v[196:197], v[164:165], v[128:129], v[196:197]
	v_pk_fma_f32 v[198:199], v[164:165], v[100:101], v[198:199]
	v_pk_fma_f32 v[200:201], v[164:165], v[104:105], v[200:201]
	v_pk_fma_f32 v[202:203], v[164:165], v[108:109], v[202:203]
	v_pk_fma_f32 v[204:205], v[164:165], v[112:113], v[204:205]
	v_pk_fma_f32 v[206:207], v[164:165], v[116:117], v[206:207]
	v_pk_fma_f32 v[208:209], v[164:165], v[120:121], v[208:209]
	v_pk_fma_f32 v[210:211], v[164:165], v[124:125], v[210:211]
	v_pk_fma_f32 v[212:213], v[164:165], v[136:137], v[212:213]
	ds_read_b128 v[98:101], v8 offset:4096
	ds_read_b128 v[102:105], v8 offset:8192
	ds_read_b128 v[106:109], v8 offset:12288
	ds_read_b128 v[110:113], v8 offset:16384
	ds_read_b128 v[114:117], v8 offset:20480
	ds_read_b128 v[118:121], v8 offset:24576
	ds_read_b128 v[122:125], v8 offset:28672
	ds_read_b128 v[126:129], v8
	ds_read_b128 v[134:137], v8 offset:32768
	v_add_u32_e32 v8, 16, v8
	s_waitcnt vmcnt(20) lgkmcnt(0)
	v_pk_fma_f32 v[196:197], v[166:167], v[126:127], v[196:197]
	v_pk_fma_f32 v[198:199], v[166:167], v[98:99], v[198:199]
	v_pk_fma_f32 v[200:201], v[166:167], v[102:103], v[200:201]
	v_pk_fma_f32 v[202:203], v[166:167], v[106:107], v[202:203]
	v_pk_fma_f32 v[204:205], v[166:167], v[110:111], v[204:205]
	v_pk_fma_f32 v[206:207], v[166:167], v[114:115], v[206:207]
	v_pk_fma_f32 v[208:209], v[166:167], v[118:119], v[208:209]
	v_pk_fma_f32 v[210:211], v[166:167], v[122:123], v[210:211]
	v_pk_fma_f32 v[212:213], v[166:167], v[134:135], v[212:213]
	v_pk_fma_f32 v[196:197], v[168:169], v[128:129], v[196:197]
	v_pk_fma_f32 v[198:199], v[168:169], v[100:101], v[198:199]
	v_pk_fma_f32 v[200:201], v[168:169], v[104:105], v[200:201]
	v_pk_fma_f32 v[202:203], v[168:169], v[108:109], v[202:203]
	v_pk_fma_f32 v[204:205], v[168:169], v[112:113], v[204:205]
	v_pk_fma_f32 v[206:207], v[168:169], v[116:117], v[206:207]
	v_pk_fma_f32 v[208:209], v[168:169], v[120:121], v[208:209]
	v_pk_fma_f32 v[210:211], v[168:169], v[124:125], v[210:211]
	v_pk_fma_f32 v[212:213], v[168:169], v[136:137], v[212:213]
	ds_read_b128 v[98:101], v8 offset:4096
	ds_read_b128 v[102:105], v8 offset:8192
	ds_read_b128 v[106:109], v8 offset:12288
	ds_read_b128 v[110:113], v8 offset:16384
	ds_read_b128 v[114:117], v8 offset:20480
	ds_read_b128 v[118:121], v8 offset:24576
	ds_read_b128 v[122:125], v8 offset:28672
	ds_read_b128 v[126:129], v8
	ds_read_b128 v[134:137], v8 offset:32768
	v_add_u32_e32 v8, 16, v8
	s_waitcnt vmcnt(16) lgkmcnt(0)
	v_pk_fma_f32 v[196:197], v[170:171], v[126:127], v[196:197]
	v_pk_fma_f32 v[198:199], v[170:171], v[98:99], v[198:199]
	v_pk_fma_f32 v[200:201], v[170:171], v[102:103], v[200:201]
	v_pk_fma_f32 v[202:203], v[170:171], v[106:107], v[202:203]
	v_pk_fma_f32 v[204:205], v[170:171], v[110:111], v[204:205]
	v_pk_fma_f32 v[206:207], v[170:171], v[114:115], v[206:207]
	v_pk_fma_f32 v[208:209], v[170:171], v[118:119], v[208:209]
	v_pk_fma_f32 v[210:211], v[170:171], v[122:123], v[210:211]
	v_pk_fma_f32 v[212:213], v[170:171], v[134:135], v[212:213]
	v_pk_fma_f32 v[196:197], v[172:173], v[128:129], v[196:197]
	v_pk_fma_f32 v[198:199], v[172:173], v[100:101], v[198:199]
	v_pk_fma_f32 v[200:201], v[172:173], v[104:105], v[200:201]
	v_pk_fma_f32 v[202:203], v[172:173], v[108:109], v[202:203]
	v_pk_fma_f32 v[204:205], v[172:173], v[112:113], v[204:205]
	v_pk_fma_f32 v[206:207], v[172:173], v[116:117], v[206:207]
	v_pk_fma_f32 v[208:209], v[172:173], v[120:121], v[208:209]
	v_pk_fma_f32 v[210:211], v[172:173], v[124:125], v[210:211]
	v_pk_fma_f32 v[212:213], v[172:173], v[136:137], v[212:213]
	ds_read_b128 v[98:101], v8 offset:4096
	ds_read_b128 v[102:105], v8 offset:8192
	ds_read_b128 v[106:109], v8 offset:12288
	ds_read_b128 v[110:113], v8 offset:16384
	ds_read_b128 v[114:117], v8 offset:20480
	ds_read_b128 v[118:121], v8 offset:24576
	ds_read_b128 v[122:125], v8 offset:28672
	ds_read_b128 v[126:129], v8
	ds_read_b128 v[134:137], v8 offset:32768
	v_add_u32_e32 v8, 16, v8
	s_waitcnt vmcnt(12) lgkmcnt(0)
	v_pk_fma_f32 v[196:197], v[174:175], v[126:127], v[196:197]
	v_pk_fma_f32 v[198:199], v[174:175], v[98:99], v[198:199]
	v_pk_fma_f32 v[200:201], v[174:175], v[102:103], v[200:201]
	v_pk_fma_f32 v[202:203], v[174:175], v[106:107], v[202:203]
	v_pk_fma_f32 v[204:205], v[174:175], v[110:111], v[204:205]
	v_pk_fma_f32 v[206:207], v[174:175], v[114:115], v[206:207]
	v_pk_fma_f32 v[208:209], v[174:175], v[118:119], v[208:209]
	v_pk_fma_f32 v[210:211], v[174:175], v[122:123], v[210:211]
	v_pk_fma_f32 v[212:213], v[174:175], v[134:135], v[212:213]
	v_pk_fma_f32 v[196:197], v[176:177], v[128:129], v[196:197]
	v_pk_fma_f32 v[198:199], v[176:177], v[100:101], v[198:199]
	v_pk_fma_f32 v[200:201], v[176:177], v[104:105], v[200:201]
	v_pk_fma_f32 v[202:203], v[176:177], v[108:109], v[202:203]
	v_pk_fma_f32 v[204:205], v[176:177], v[112:113], v[204:205]
	v_pk_fma_f32 v[206:207], v[176:177], v[116:117], v[206:207]
	v_pk_fma_f32 v[208:209], v[176:177], v[120:121], v[208:209]
	v_pk_fma_f32 v[210:211], v[176:177], v[124:125], v[210:211]
	v_pk_fma_f32 v[212:213], v[176:177], v[136:137], v[212:213]
	ds_read_b128 v[98:101], v8 offset:4096
	ds_read_b128 v[102:105], v8 offset:8192
	ds_read_b128 v[106:109], v8 offset:12288
	ds_read_b128 v[110:113], v8 offset:16384
	ds_read_b128 v[114:117], v8 offset:20480
	ds_read_b128 v[118:121], v8 offset:24576
	ds_read_b128 v[122:125], v8 offset:28672
	ds_read_b128 v[126:129], v8
	ds_read_b128 v[134:137], v8 offset:32768
	v_add_u32_e32 v8, 16, v8
	s_waitcnt vmcnt(8) lgkmcnt(0)
	v_pk_fma_f32 v[196:197], v[178:179], v[126:127], v[196:197]
	v_pk_fma_f32 v[198:199], v[178:179], v[98:99], v[198:199]
	v_pk_fma_f32 v[200:201], v[178:179], v[102:103], v[200:201]
	v_pk_fma_f32 v[202:203], v[178:179], v[106:107], v[202:203]
	v_pk_fma_f32 v[204:205], v[178:179], v[110:111], v[204:205]
	v_pk_fma_f32 v[206:207], v[178:179], v[114:115], v[206:207]
	v_pk_fma_f32 v[208:209], v[178:179], v[118:119], v[208:209]
	v_pk_fma_f32 v[210:211], v[178:179], v[122:123], v[210:211]
	v_pk_fma_f32 v[212:213], v[178:179], v[134:135], v[212:213]
	v_pk_fma_f32 v[196:197], v[180:181], v[128:129], v[196:197]
	v_pk_fma_f32 v[198:199], v[180:181], v[100:101], v[198:199]
	v_pk_fma_f32 v[200:201], v[180:181], v[104:105], v[200:201]
	v_pk_fma_f32 v[202:203], v[180:181], v[108:109], v[202:203]
	v_pk_fma_f32 v[204:205], v[180:181], v[112:113], v[204:205]
	v_pk_fma_f32 v[206:207], v[180:181], v[116:117], v[206:207]
	v_pk_fma_f32 v[208:209], v[180:181], v[120:121], v[208:209]
	v_pk_fma_f32 v[210:211], v[180:181], v[124:125], v[210:211]
	v_pk_fma_f32 v[212:213], v[180:181], v[136:137], v[212:213]
	ds_read_b128 v[98:101], v8 offset:4096
	ds_read_b128 v[102:105], v8 offset:8192
	ds_read_b128 v[106:109], v8 offset:12288
	ds_read_b128 v[110:113], v8 offset:16384
	ds_read_b128 v[114:117], v8 offset:20480
	ds_read_b128 v[118:121], v8 offset:24576
	ds_read_b128 v[122:125], v8 offset:28672
	ds_read_b128 v[126:129], v8
	ds_read_b128 v[134:137], v8 offset:32768
	v_add_u32_e32 v8, 16, v8
	s_waitcnt vmcnt(4) lgkmcnt(0)
	v_pk_fma_f32 v[196:197], v[182:183], v[126:127], v[196:197]
	v_pk_fma_f32 v[198:199], v[182:183], v[98:99], v[198:199]
	v_pk_fma_f32 v[200:201], v[182:183], v[102:103], v[200:201]
	v_pk_fma_f32 v[202:203], v[182:183], v[106:107], v[202:203]
	v_pk_fma_f32 v[204:205], v[182:183], v[110:111], v[204:205]
	v_pk_fma_f32 v[206:207], v[182:183], v[114:115], v[206:207]
	v_pk_fma_f32 v[208:209], v[182:183], v[118:119], v[208:209]
	v_pk_fma_f32 v[210:211], v[182:183], v[122:123], v[210:211]
	v_pk_fma_f32 v[212:213], v[182:183], v[134:135], v[212:213]
	v_pk_fma_f32 v[196:197], v[184:185], v[128:129], v[196:197]
	v_pk_fma_f32 v[198:199], v[184:185], v[100:101], v[198:199]
	v_pk_fma_f32 v[200:201], v[184:185], v[104:105], v[200:201]
	v_pk_fma_f32 v[202:203], v[184:185], v[108:109], v[202:203]
	v_pk_fma_f32 v[204:205], v[184:185], v[112:113], v[204:205]
	v_pk_fma_f32 v[206:207], v[184:185], v[116:117], v[206:207]
	v_pk_fma_f32 v[208:209], v[184:185], v[120:121], v[208:209]
	v_pk_fma_f32 v[210:211], v[184:185], v[124:125], v[210:211]
	v_pk_fma_f32 v[212:213], v[184:185], v[136:137], v[212:213]
	ds_read_b128 v[98:101], v8 offset:4096
	ds_read_b128 v[102:105], v8 offset:8192
	ds_read_b128 v[106:109], v8 offset:12288
	ds_read_b128 v[110:113], v8 offset:16384
	ds_read_b128 v[114:117], v8 offset:20480
	ds_read_b128 v[118:121], v8 offset:24576
	ds_read_b128 v[122:125], v8 offset:28672
	ds_read_b128 v[126:129], v8
	ds_read_b128 v[134:137], v8 offset:32768
	v_add_u32_e32 v8, 16, v8
	s_waitcnt vmcnt(0) lgkmcnt(0)
	v_pk_fma_f32 v[196:197], v[186:187], v[126:127], v[196:197]
	v_pk_fma_f32 v[198:199], v[186:187], v[98:99], v[198:199]
	v_pk_fma_f32 v[200:201], v[186:187], v[102:103], v[200:201]
	v_pk_fma_f32 v[202:203], v[186:187], v[106:107], v[202:203]
	v_pk_fma_f32 v[204:205], v[186:187], v[110:111], v[204:205]
	v_pk_fma_f32 v[206:207], v[186:187], v[114:115], v[206:207]
	v_pk_fma_f32 v[208:209], v[186:187], v[118:119], v[208:209]
	v_pk_fma_f32 v[210:211], v[186:187], v[122:123], v[210:211]
	v_pk_fma_f32 v[212:213], v[186:187], v[134:135], v[212:213]
	v_pk_fma_f32 v[196:197], v[188:189], v[128:129], v[196:197]
	v_pk_fma_f32 v[198:199], v[188:189], v[100:101], v[198:199]
	v_pk_fma_f32 v[200:201], v[188:189], v[104:105], v[200:201]
	v_pk_fma_f32 v[202:203], v[188:189], v[108:109], v[202:203]
	v_pk_fma_f32 v[204:205], v[188:189], v[112:113], v[204:205]
	v_pk_fma_f32 v[206:207], v[188:189], v[116:117], v[206:207]
	v_pk_fma_f32 v[208:209], v[188:189], v[120:121], v[208:209]
	v_pk_fma_f32 v[210:211], v[188:189], v[124:125], v[210:211]
	v_pk_fma_f32 v[212:213], v[188:189], v[136:137], v[212:213]
	v_add_f32_e32 v4, v196, v197
	v_add_f32_e32 v5, v198, v199
	v_add_f32_e32 v68, v200, v201
	v_add_f32_e32 v69, v202, v203
	v_add_f32_e32 v70, v204, v205
	v_add_f32_e32 v71, v206, v207
	v_add_f32_e32 v72, v208, v209
	v_add_f32_e32 v73, v210, v211
	v_add_f32_e32 v23, v212, v213
	v_add_u32_e32 v2, 0x9000, v76
	ds_write2_b32 v2, v4, v5 offset1:32
	ds_write2_b32 v2, v68, v69 offset0:64 offset1:96
	ds_write2_b32 v2, v70, v71 offset0:128 offset1:160
	ds_write2_b32 v2, v72, v73 offset0:192 offset1:224
	ds_write_b32 v76, v23 offset:37888
	v_mov_b32_e32 v2, s63
	v_mov_b32_e32 v4, s75
	s_waitcnt lgkmcnt(0)
	s_barrier
	ds_read_b64 v[2:3], v2
	ds_read_b64 v[4:5], v4
	v_lshl_or_b32 v8, v1, 5, v74
	v_add_u32_e32 v8, 0xfffdd800, v8
	s_mov_b64 s[52:53], 0
	s_waitcnt lgkmcnt(1)
	v_lshl_add_u64 v[2:3], v[2:3], 0, s[36:37]
	s_waitcnt lgkmcnt(0)
	v_lshl_add_u64 v[4:5], v[8:9], 2, v[4:5]
	v_mov_b32_e32 v8, v84
	v_mov_b32_e32 v23, v83
	v_mov_b32_e32 v61, v82
	v_mov_b32_e32 v65, v89

.LBB0_43:
	s_andn2_saveexec_b64 s[50:51], s[50:51]
	s_cbranch_execz .LBB0_47
	v_add_u16_e32 v8, 0xf180, v1
	v_mul_u32_u24_e32 v23, 0xba2f, v8
	v_lshrrev_b32_e32 v23, 21, v23
	v_mov_b32_e32 v2, s76
	v_mov_b32_e32 v4, s63
	v_mul_lo_u16_e32 v61, 44, v23
	ds_read_b64 v[2:3], v2
	ds_read_b64 v[4:5], v4
	v_sub_u16_e32 v8, v8, v61
	v_lshlrev_b16_e32 v61, 6, v8
	v_or_b32_e32 v8, v77, v61
	v_lshlrev_b32_e32 v8, 12, v8
	s_waitcnt lgkmcnt(0)
	v_add_co_u32_e32 v2, vcc, v2, v8
	v_addc_co_u32_e32 v3, vcc, v3, v9, vcc
	v_lshlrev_b32_e32 v8, 8, v23
	v_add_co_u32_e32 v2, vcc, v2, v8
	v_addc_co_u32_e32 v3, vcc, v3, v9, vcc
	v_lshlrev_b32_e32 v8, 2, v6
	v_add_co_u32_e32 v2, vcc, v2, v8
	v_addc_co_u32_e32 v3, vcc, v3, v9, vcc
	v_add_co_u32_e32 v68, vcc, s77, v2
	v_mov_b32_e32 v71, v9
	s_nop 0
	v_addc_co_u32_e32 v69, vcc, 0, v3, vcc
	flat_load_dwordx4 v[98:101], v[2:3] nt
	flat_load_dwordx4 v[102:105], v[68:69] nt
	v_add_co_u32_e32 v68, vcc, s78, v2
	v_lshl_add_u64 v[72:73], v[4:5], 0, v[12:13]
	s_nop 0
	v_addc_co_u32_e32 v69, vcc, 0, v3, vcc
	flat_load_dwordx4 v[106:109], v[68:69] nt
	v_add_co_u32_e32 v2, vcc, s79, v2
	s_mov_b64 s[52:53], 0
	s_nop 0
	v_addc_co_u32_e32 v3, vcc, 0, v3, vcc
	flat_load_dwordx4 v[110:113], v[2:3] nt
	v_lshlrev_b32_e32 v2, 6, v23
	v_or_b32_e32 v8, v90, v2
	v_or_b32_e32 v23, v91, v2
	v_or_b32_e32 v70, v92, v2
	v_mov_b32_e32 v3, v9
	v_mov_b32_e32 v69, v9
	v_or_b32_e32 v118, v75, v2
	v_mul_u32_u24_e32 v2, 0x1600, v8
	v_mul_u32_u24_e32 v68, 0x1600, v23
	v_mul_u32_u24_e32 v70, 0x1600, v70
	v_lshlrev_b32_e32 v8, 1, v61
	v_lshl_add_u64 v[2:3], v[8:9], 0, v[2:3]
	v_lshl_add_u64 v[4:5], v[8:9], 0, v[68:69]
	v_lshl_add_u64 v[68:69], v[8:9], 0, v[70:71]
	v_mad_u64_u32 v[70:71], s[54:55], v118, s80, v[8:9]
	v_lshl_add_u64 v[2:3], v[72:73], 0, v[2:3]
	v_lshl_add_u64 v[4:5], v[72:73], 0, v[4:5]
	v_lshl_add_u64 v[68:69], v[72:73], 0, v[68:69]
	v_lshl_add_u64 v[70:71], v[72:73], 0, v[70:71]
	v_mov_b32_e32 v8, v85
	v_add_u32_e32 v65, 0x1040, v78
	v_add_u32_e32 v66, 0x1048, v78
	v_add_u32_e32 v114, 0x2080, v78
	v_add_u32_e32 v115, 0x2088, v78
	v_add_u32_e32 v116, 0x30c0, v78
	v_add_u32_e32 v117, 0x30c8, v78
	s_waitcnt vmcnt(0) lgkmcnt(0)
	ds_write2_b32 v78, v98, v99 offset1:1
	ds_write2_b32 v78, v100, v101 offset0:2 offset1:3
	ds_write2_b32 v65, v102, v103 offset1:1
	ds_write2_b32 v66, v104, v105 offset1:1
	ds_write2_b32 v114, v106, v107 offset1:1
	ds_write2_b32 v115, v108, v109 offset1:1
	ds_write2_b32 v116, v110, v111 offset1:1
	ds_write2_b32 v117, v112, v113 offset1:1
	s_waitcnt lgkmcnt(0)
	s_barrier

.LBB0_48:
	s_andn2_saveexec_b64 s[48:49], s[48:49]
	s_cbranch_execz .LBB0_52
	v_mov_b32_e32 v2, s82
	v_mov_b32_e32 v4, s63
	ds_read_b64 v[2:3], v2
	ds_read_b64 v[4:5], v4
	v_lshlrev_b32_e32 v8, 6, v1
	v_and_or_b32 v8, v8, s59, v77
	v_lshl_add_u32 v61, v1, 2, v96
	v_mul_u32_u24_e32 v8, 0x1600, v8
	v_and_b32_e32 v61, 0x3ffc0, v61
	v_lshlrev_b32_e32 v68, 2, v8
	v_mov_b32_e32 v69, v9
	s_waitcnt lgkmcnt(0)
	v_add_co_u32_e32 v2, vcc, v2, v68
	v_addc_co_u32_e32 v3, vcc, v3, v69, vcc
	v_lshlrev_b32_e32 v68, 2, v61
	v_add_co_u32_e32 v2, vcc, v2, v68
	v_addc_co_u32_e32 v3, vcc, v3, v69, vcc
	v_lshlrev_b32_e32 v68, 2, v6
	v_add_co_u32_e32 v2, vcc, v2, v68
	v_addc_co_u32_e32 v3, vcc, v3, v69, vcc
	v_add_co_u32_e32 v68, vcc, s81, v2
	v_mov_b32_e32 v71, v9
	s_nop 0
	v_addc_co_u32_e32 v69, vcc, 0, v3, vcc
	flat_load_dwordx4 v[98:101], v[2:3] nt
	flat_load_dwordx4 v[102:105], v[68:69] nt
	v_add_co_u32_e32 v68, vcc, s83, v2
	v_mov_b32_e32 v73, v9
	s_nop 0
	v_addc_co_u32_e32 v69, vcc, 0, v3, vcc
	flat_load_dwordx4 v[106:109], v[68:69] nt
	v_add_co_u32_e32 v2, vcc, s84, v2
	v_lshl_add_u64 v[114:115], v[4:5], 0, v[14:15]
	s_nop 0
	v_addc_co_u32_e32 v3, vcc, 0, v3, vcc
	flat_load_dwordx4 v[110:113], v[2:3] nt
	v_and_b32_e32 v2, 0x3ffc0, v93
	v_or_b32_e32 v3, v90, v2
	v_or_b32_e32 v68, v91, v2
	v_or_b32_e32 v70, v92, v2
	v_or_b32_e32 v2, v75, v2
	v_mov_b32_e32 v69, v9
	v_lshl_or_b32 v8, v3, 11, v23
	v_lshl_or_b32 v68, v68, 11, v23
	v_lshl_or_b32 v70, v70, 11, v23
	v_lshl_or_b32 v72, v2, 11, v23
	s_mov_b64 s[50:51], 0
	v_lshl_add_u64 v[2:3], v[114:115], 0, v[8:9]
	v_lshl_add_u64 v[4:5], v[114:115], 0, v[68:69]
	v_lshl_add_u64 v[68:69], v[114:115], 0, v[70:71]
	v_lshl_add_u64 v[70:71], v[114:115], 0, v[72:73]
	v_mov_b32_e32 v8, v85
	v_add_u32_e32 v61, 0x1040, v78
	v_add_u32_e32 v65, 0x1048, v78
	v_add_u32_e32 v66, 0x2080, v78
	v_add_u32_e32 v116, 0x2088, v78
	v_add_u32_e32 v117, 0x30c0, v78
	v_add_u32_e32 v118, 0x30c8, v78
	s_waitcnt vmcnt(0) lgkmcnt(0)
	ds_write2_b32 v78, v98, v99 offset1:1
	ds_write2_b32 v78, v100, v101 offset0:2 offset1:3
	ds_write2_b32 v61, v102, v103 offset1:1
	ds_write2_b32 v65, v104, v105 offset1:1
	ds_write2_b32 v66, v106, v107 offset1:1
	ds_write2_b32 v116, v108, v109 offset1:1
	ds_write2_b32 v117, v110, v111 offset1:1
	ds_write2_b32 v118, v112, v113 offset1:1
	s_waitcnt lgkmcnt(0)
	s_barrier

.LBB0_53:
	s_andn2_saveexec_b64 s[46:47], s[46:47]
	s_cbranch_execz .LBB0_57
	v_mov_b32_e32 v23, s85
	v_mov_b32_e32 v61, s63
	ds_read_b64 v[70:71], v23
	ds_read_b64 v[72:73], v61
	v_lshlrev_b32_e32 v23, 6, v1
	v_and_or_b32 v23, v23, s59, v77
	v_lshlrev_b32_e32 v98, 12, v23
	v_mov_b32_e32 v99, v9
	v_lshlrev_b32_e32 v23, 4, v1
	s_waitcnt lgkmcnt(0)
	v_add_co_u32_e32 v70, vcc, v70, v98
	v_addc_co_u32_e32 v71, vcc, v71, v99, vcc
	v_and_b32_e32 v98, 0xf00, v23
	v_add_co_u32_e32 v70, vcc, v70, v98
	v_addc_co_u32_e32 v71, vcc, v71, v99, vcc
	v_lshlrev_b32_e32 v98, 2, v6
	v_add_co_u32_e32 v70, vcc, v70, v98
	v_addc_co_u32_e32 v71, vcc, v71, v99, vcc
	v_add_co_u32_e32 v102, vcc, s77, v70
	v_lshl_add_u64 v[72:73], v[72:73], 0, v[16:17]
	s_nop 0
	v_addc_co_u32_e32 v103, vcc, 0, v71, vcc
	flat_load_dwordx4 v[98:101], v[70:71] nt
	s_nop 0
	flat_load_dwordx4 v[102:105], v[102:103] nt
	v_add_co_u32_e32 v106, vcc, s78, v70
	s_mov_b64 s[48:49], 0
	s_nop 0
	v_addc_co_u32_e32 v107, vcc, 0, v71, vcc
	flat_load_dwordx4 v[106:109], v[106:107] nt
	v_add_co_u32_e32 v70, vcc, s79, v70
	v_lshl_add_u64 v[2:3], v[72:73], 0, v[2:3]
	s_nop 0
	v_addc_co_u32_e32 v71, vcc, 0, v71, vcc
	flat_load_dwordx4 v[110:113], v[70:71] nt
	v_lshl_add_u64 v[70:71], v[72:73], 0, v[8:9]
	v_lshl_add_u64 v[4:5], v[72:73], 0, v[4:5]
	v_lshl_add_u64 v[68:69], v[72:73], 0, v[68:69]
	v_mov_b32_e32 v8, v85
	v_add_u32_e32 v23, 0x1040, v78
	v_add_u32_e32 v61, 0x1048, v78
	v_add_u32_e32 v65, 0x2080, v78
	v_add_u32_e32 v66, 0x2088, v78
	v_add_u32_e32 v114, 0x30c0, v78
	v_add_u32_e32 v115, 0x30c8, v78
	s_waitcnt vmcnt(0) lgkmcnt(0)
	ds_write2_b32 v78, v98, v99 offset1:1
	ds_write2_b32 v78, v100, v101 offset0:2 offset1:3
	ds_write2_b32 v23, v102, v103 offset1:1
	ds_write2_b32 v61, v104, v105 offset1:1
	ds_write2_b32 v65, v106, v107 offset1:1
	ds_write2_b32 v66, v108, v109 offset1:1
	ds_write2_b32 v114, v110, v111 offset1:1
	ds_write2_b32 v115, v112, v113 offset1:1
	s_waitcnt lgkmcnt(0)
	s_barrier

.LBB0_58:
	s_andn2_saveexec_b64 s[44:45], s[44:45]
	s_cbranch_execz .LBB0_62
	v_mov_b32_e32 v23, s86
	v_mov_b32_e32 v61, s63
	ds_read_b64 v[70:71], v23
	ds_read_b64 v[72:73], v61
	v_lshlrev_b32_e32 v23, 6, v1
	v_and_or_b32 v23, v23, s59, v77
	v_lshlrev_b32_e32 v98, 12, v23
	v_mov_b32_e32 v99, v9
	v_lshlrev_b32_e32 v23, 4, v1
	s_waitcnt lgkmcnt(0)
	v_add_co_u32_e32 v70, vcc, v70, v98
	v_addc_co_u32_e32 v71, vcc, v71, v99, vcc
	v_and_b32_e32 v98, 0xf00, v23
	v_add_co_u32_e32 v70, vcc, v70, v98
	v_addc_co_u32_e32 v71, vcc, v71, v99, vcc
	v_lshlrev_b32_e32 v98, 2, v6
	v_add_co_u32_e32 v70, vcc, v70, v98
	v_addc_co_u32_e32 v71, vcc, v71, v99, vcc
	v_add_co_u32_e32 v102, vcc, s77, v70
	v_lshl_add_u64 v[72:73], v[72:73], 0, v[18:19]
	s_nop 0
	v_addc_co_u32_e32 v103, vcc, 0, v71, vcc
	flat_load_dwordx4 v[98:101], v[70:71] nt
	s_nop 0
	flat_load_dwordx4 v[102:105], v[102:103] nt
	v_add_co_u32_e32 v106, vcc, s78, v70
	s_mov_b64 s[46:47], 0
	s_nop 0
	v_addc_co_u32_e32 v107, vcc, 0, v71, vcc
	flat_load_dwordx4 v[106:109], v[106:107] nt
	v_add_co_u32_e32 v70, vcc, s79, v70
	v_lshl_add_u64 v[2:3], v[72:73], 0, v[2:3]
	s_nop 0
	v_addc_co_u32_e32 v71, vcc, 0, v71, vcc
	flat_load_dwordx4 v[110:113], v[70:71] nt
	v_lshl_add_u64 v[70:71], v[72:73], 0, v[8:9]
	v_lshl_add_u64 v[4:5], v[72:73], 0, v[4:5]
	v_lshl_add_u64 v[68:69], v[72:73], 0, v[68:69]
	v_mov_b32_e32 v8, v85
	v_add_u32_e32 v23, 0x1040, v78
	v_add_u32_e32 v61, 0x1048, v78
	v_add_u32_e32 v65, 0x2080, v78
	v_add_u32_e32 v66, 0x2088, v78
	v_add_u32_e32 v114, 0x30c0, v78
	v_add_u32_e32 v115, 0x30c8, v78
	s_waitcnt vmcnt(0) lgkmcnt(0)
	ds_write2_b32 v78, v98, v99 offset1:1
	ds_write2_b32 v78, v100, v101 offset0:2 offset1:3
	ds_write2_b32 v23, v102, v103 offset1:1
	ds_write2_b32 v61, v104, v105 offset1:1
	ds_write2_b32 v65, v106, v107 offset1:1
	ds_write2_b32 v66, v108, v109 offset1:1
	ds_write2_b32 v114, v110, v111 offset1:1
	ds_write2_b32 v115, v112, v113 offset1:1
	s_waitcnt lgkmcnt(0)
	s_barrier

.LBB0_63:
	s_andn2_saveexec_b64 s[42:43], s[42:43]
	s_cbranch_execz .LBB0_67
	v_mov_b32_e32 v3, s87
	v_mov_b32_e32 v8, s63
	ds_read_b64 v[4:5], v3
	ds_read_b64 v[68:69], v8
	v_lshlrev_b32_e32 v3, 6, v1
	v_lshlrev_b32_e32 v23, 3, v1
	v_and_or_b32 v3, v3, s88, v77
	v_bitop3_b32 v61, v23, s70, v97 bitop3:0x6c
	v_lshlrev_b32_e32 v8, 12, v3
	s_waitcnt lgkmcnt(0)
	v_add_co_u32_e32 v4, vcc, v4, v8
	v_addc_co_u32_e32 v5, vcc, v5, v9, vcc
	v_lshlrev_b32_e32 v8, 2, v61
	v_add_co_u32_e32 v4, vcc, v4, v8
	v_addc_co_u32_e32 v5, vcc, v5, v9, vcc
	v_lshlrev_b32_e32 v8, 2, v6
	v_add_co_u32_e32 v4, vcc, v4, v8
	v_addc_co_u32_e32 v5, vcc, v5, v9, vcc
	v_add_co_u32_e32 v70, vcc, s77, v4
	v_and_b32_e32 v2, 7, v2
	s_nop 0
	v_addc_co_u32_e32 v71, vcc, 0, v5, vcc
	flat_load_dwordx4 v[98:101], v[4:5] nt
	flat_load_dwordx4 v[102:105], v[70:71] nt
	v_add_co_u32_e32 v70, vcc, s78, v4
	v_lshlrev_b32_e32 v115, 7, v2
	s_nop 0
	v_addc_co_u32_e32 v71, vcc, 0, v5, vcc
	flat_load_dwordx4 v[106:109], v[70:71] nt
	v_add_co_u32_e32 v4, vcc, s79, v4
	v_and_b32_e32 v2, 0x7c0, v23
	s_nop 0
	v_addc_co_u32_e32 v5, vcc, 0, v5, vcc
	flat_load_dwordx4 v[110:113], v[4:5] nt
	v_bitop3_b32 v3, v90, v2, s70 bitop3:0xf6
	v_bitop3_b32 v4, v91, v2, s70 bitop3:0xf6
	v_lshl_add_u64 v[70:71], v[68:69], 0, v[20:21]
	v_lshl_or_b32 v8, v3, 10, v115
	v_bitop3_b32 v23, v92, v2, s70 bitop3:0xf6
	v_bitop3_b32 v116, v75, v2, s70 bitop3:0xf6
	v_lshl_add_u64 v[2:3], v[70:71], 0, v[8:9]
	v_lshl_or_b32 v8, v4, 10, v115
	v_lshl_add_u64 v[4:5], v[70:71], 0, v[8:9]
	v_lshl_or_b32 v8, v23, 10, v115
	v_lshl_add_u64 v[68:69], v[70:71], 0, v[8:9]
	v_lshl_or_b32 v8, v116, 10, v115
	s_mov_b64 s[44:45], 0
	v_lshl_add_u64 v[70:71], v[70:71], 0, v[8:9]
	v_mov_b32_e32 v8, v85
	v_add_u32_e32 v61, 0x1040, v78
	v_add_u32_e32 v65, 0x1048, v78
	v_add_u32_e32 v66, 0x2080, v78
	v_add_u32_e32 v72, 0x2088, v78
	v_add_u32_e32 v73, 0x30c0, v78
	v_add_u32_e32 v114, 0x30c8, v78
	s_waitcnt vmcnt(0) lgkmcnt(0)
	ds_write2_b32 v78, v98, v99 offset1:1
	ds_write2_b32 v78, v100, v101 offset0:2 offset1:3
	ds_write2_b32 v61, v102, v103 offset1:1
	ds_write2_b32 v65, v104, v105 offset1:1
	ds_write2_b32 v66, v106, v107 offset1:1
	ds_write2_b32 v72, v108, v109 offset1:1
	ds_write2_b32 v73, v110, v111 offset1:1
	ds_write2_b32 v114, v112, v113 offset1:1
	s_waitcnt lgkmcnt(0)
	s_barrier

.LBB0_68:
	v_mov_b32_e32 v2, s89
	v_mov_b32_e32 v4, s63
	ds_read_b64 v[2:3], v2
	ds_read_b64 v[72:73], v4
	v_ashrrev_i32_e32 v4, 31, v1
	v_lshrrev_b32_e32 v4, 28, v4
	v_add_u32_e32 v4, v1, v4
	v_and_b32_e32 v5, 0x3fffff0, v4
	v_sub_u32_e32 v5, v1, v5
	v_lshlrev_b32_e32 v110, 6, v5
	v_or_b32_e32 v5, v110, v77
	v_lshlrev_b32_e32 v4, 2, v4
	v_mul_lo_u32 v68, v5, s90
	v_and_b32_e32 v4, 0xffffffc0, v4
	v_ashrrev_i32_e32 v69, 31, v68
	s_waitcnt lgkmcnt(0)
	v_lshl_add_u64 v[2:3], v[68:69], 2, v[2:3]
	v_ashrrev_i32_e32 v5, 31, v4
	v_lshl_add_u64 v[2:3], v[4:5], 2, v[2:3]
	v_lshlrev_b32_e32 v8, 2, v6
	v_add_co_u32_e32 v2, vcc, v2, v8
	v_addc_co_u32_e32 v3, vcc, v3, v9, vcc
	v_add_co_u32_e32 v98, vcc, s91, v2
	v_ashrrev_i32_e32 v111, 31, v110
	s_nop 0
	v_addc_co_u32_e32 v99, vcc, 0, v3, vcc
	flat_load_dwordx4 v[68:71], v[2:3] nt
	s_nop 0
	flat_load_dwordx4 v[98:101], v[98:99] nt
	v_add_co_u32_e32 v102, vcc, s92, v2
	v_add_u32_e32 v5, 0x1040, v78
	s_nop 0
	v_addc_co_u32_e32 v103, vcc, 0, v3, vcc
	flat_load_dwordx4 v[102:105], v[102:103] nt
	v_add_co_u32_e32 v2, vcc, s93, v2
	v_mov_b32_e32 v23, v9
	s_nop 0
	v_addc_co_u32_e32 v3, vcc, 0, v3, vcc
	flat_load_dwordx4 v[106:109], v[2:3] nt
	v_lshl_add_u64 v[2:3], v[110:111], 1, v[72:73]
	s_mov_b32 s34, 0
	v_add_u32_e32 v8, 0x1048, v78
	v_add_u32_e32 v61, 0x2080, v78
	v_add_u32_e32 v65, 0x2088, v78
	v_add_u32_e32 v66, 0x30c0, v78
	v_add_u32_e32 v112, 0x30c8, v78
	v_or_b32_e32 v4, v75, v4
	v_lshl_add_u64 v[2:3], v[2:3], 0, v[22:23]
	s_waitcnt vmcnt(0) lgkmcnt(0)
	ds_write2_b32 v78, v68, v69 offset1:1
	ds_write2_b32 v78, v70, v71 offset0:2 offset1:3
	ds_write2_b32 v5, v98, v99 offset1:1
	ds_write2_b32 v8, v100, v101 offset1:1
	ds_write2_b32 v61, v102, v103 offset1:1
	ds_write2_b32 v65, v104, v105 offset1:1
	ds_write2_b32 v66, v106, v107 offset1:1
	ds_write2_b32 v112, v108, v109 offset1:1
	v_mov_b32_e32 v5, v85
	s_waitcnt lgkmcnt(0)
	s_barrier
